# prep token loop: five consecutive tokens per wave, the previous-token row is the preceding token's row kept in registers (12 fewer loads per wave per direction)
# baseline (speedup 1.0000x reference)
.LBB0_485:
	s_or_b64 exec, exec, s[6:7]
	v_lshl_add_u32 v0, s0, 8, v32
	v_readlane_b32 s60, v253, 46
	v_ashrrev_i32_e32 v1, 31, v0
	v_readlane_b32 s61, v253, 47
	v_readlane_b32 s62, v253, 48
	v_readlane_b32 s63, v253, 49
	v_readlane_b32 s64, v253, 50
	v_readlane_b32 s65, v253, 51
	v_readlane_b32 s66, v253, 52
	v_readlane_b32 s67, v253, 53
	v_lshlrev_b64 v[2:3], 2, v[0:1]
	v_readlane_b32 s52, v253, 62
	v_lshl_add_u32 v0, s0, 9, v0
	v_readlane_b32 s70, v253, 56
	v_readlane_b32 s71, v253, 57
	v_readlane_b32 s74, v253, 60
	v_readlane_b32 s75, v253, 61
	v_readlane_b32 s54, v254, 0
	v_readlane_b32 s55, v254, 1
	v_ashrrev_i32_e32 v1, 31, v0
	v_lshl_add_u64 v[4:5], s[74:75], 0, v[2:3]
	v_lshl_add_u64 v[2:3], s[54:55], 0, v[2:3]
	s_mul_i32 s1, s0, 0x300
	v_lshl_add_u64 v[0:1], v[0:1], 2, s[70:71]
	v_readfirstlane_b32 s82, v160
	s_lshr_b32 s82, s82, 6
	s_lshl_b32 s82, s82, 10
	s_add_i32 s82, s82, 0xd000
	v_add_u32_e32 v249, s82, v251
	ds_write_b128 v249, v[222:225]
	s_waitcnt lgkmcnt(0)
	s_barrier
	s_xor_b64 s[18:19], s[16:17], -1
	v_readlane_b32 s22, v254, 34
	v_readlane_b32 s72, v254, 43
	v_readlane_b32 s73, v254, 44
	v_readlane_b32 s92, v254, 49
	v_readfirstlane_b32 s0, v160
	s_lshr_b32 s0, s0, 6
	s_and_b32 s0, s0, 3
	s_mul_i32 s53, s51, 20
	s_mul_i32 s0, s0, 5
	s_add_i32 s53, s53, s0
	s_lshl_b32 s0, s0, 10
	s_add_i32 s92, s92, s0
	v_and_b32_e32 v250, 63, v160
	v_lshlrev_b32_e32 v251, 4, v250
	v_lshlrev_b32_e32 v250, 3, v250
	v_add_u32_e32 v31, s92, v251
	s_add_u32 s28, s72, 0x664a000
	s_addc_u32 s29, s73, 0
	s_add_u32 s34, s72, 0xaeca000
	s_addc_u32 s35, s73, 0
	s_add_u32 s42, s72, 0x13aca000
	s_addc_u32 s43, s73, 0
	s_waitcnt lgkmcnt(0)
	s_cmp_eq_u64 s[16:17], 0
	s_cbranch_scc1 .Lprep_tok_d1
	ds_read_b128 v[210:213], v251 offset:53248
	ds_read_b128 v[214:217], v251 offset:54272
	ds_read_b128 v[218:221], v251 offset:55296
	ds_read_b128 v[198:201], v251 offset:56320
	ds_read_b128 v[194:197], v251 offset:57344
	ds_read_b128 v[190:193], v251 offset:58368
	ds_read_b128 v[202:205], v251 offset:59392
	ds_read_b128 v[206:209], v251 offset:60416
	s_add_i32 s56, s53, 0
	s_cmpk_lt_i32 s56, 0x2000
	s_movk_i32 s0, 0x3ff
	s_cselect_b32 s0, 0xff, s0
	s_and_b32 s1, s56, s0
	s_cmp_lg_u32 s1, 0
	s_cselect_b32 s59, 1.0, 0
	s_cselect_b32 s1, -1, 0
	s_add_i32 s1, s56, s1
	s_mul_i32 s0, s56, 0x1d00
	s_add_u32 s76, s28, s0
	s_addc_u32 s77, s29, 0
	s_mul_i32 s0, s1, 0x1d00
	s_add_u32 s78, s28, s0
	s_addc_u32 s79, s29, 0
	global_load_dwordx2 v[222:223], v250, s[76:77] offset:0
	global_load_dwordx2 v[224:225], v250, s[76:77] offset:512
	global_load_dwordx2 v[226:227], v250, s[76:77] offset:1024
	global_load_dwordx2 v[228:229], v250, s[78:79] offset:0
	global_load_dwordx2 v[230:231], v250, s[78:79] offset:512
	global_load_dwordx2 v[232:233], v250, s[78:79] offset:1024
	s_add_i32 s57, s53, 1
	s_cmpk_lt_i32 s57, 0x2000
	s_movk_i32 s0, 0x3ff
	s_cselect_b32 s0, 0xff, s0
	s_and_b32 s1, s57, s0
	s_cmp_lg_u32 s1, 0
	s_cselect_b32 s60, 1.0, 0
	s_cselect_b32 s1, -1, 0
	s_add_i32 s1, s57, s1
	s_mul_i32 s0, s57, 0x1d00
	s_add_u32 s80, s28, s0
	s_addc_u32 s81, s29, 0
	s_mul_i32 s0, s1, 0x1d00
	s_add_u32 s82, s28, s0
	s_addc_u32 s83, s29, 0
	global_load_dwordx2 v[236:237], v250, s[80:81] offset:0
	global_load_dwordx2 v[238:239], v250, s[80:81] offset:512
	global_load_dwordx2 v[240:241], v250, s[80:81] offset:1024
	s_add_i32 s58, s53, 2
	s_cmpk_lt_i32 s58, 0x2000
	s_movk_i32 s0, 0x3ff
	s_cselect_b32 s0, 0xff, s0
	s_and_b32 s1, s58, s0
	s_cmp_lg_u32 s1, 0
	s_cselect_b32 s61, 1.0, 0
	s_cselect_b32 s1, -1, 0
	s_add_i32 s1, s58, s1
	s_mul_i32 s0, s58, 0x1d00
	s_add_u32 s84, s28, s0
	s_addc_u32 s85, s29, 0
	s_mul_i32 s0, s1, 0x1d00
	s_add_u32 s96, s28, s0
	s_addc_u32 s97, s29, 0
	global_load_dwordx2 v[0:1], v250, s[84:85] offset:0
	global_load_dwordx2 v[2:3], v250, s[84:85] offset:512
	global_load_dwordx2 v[4:5], v250, s[84:85] offset:1024
	ds_read_b128 v[14:17], v31 offset:0
	ds_read_b128 v[18:21], v31 offset:20480
	ds_read_b128 v[22:25], v31 offset:1024
	ds_read_b128 v[26:29], v31 offset:21504
	s_waitcnt lgkmcnt(4)
	s_waitcnt vmcnt(6)
	v_mov_b32_e32 v242, v222
	v_mov_b32_e32 v243, v223
	v_mov_b32_e32 v244, v224
	v_mov_b32_e32 v245, v225
	v_mov_b32_e32 v246, v226
	v_mov_b32_e32 v247, v227
	v_lshlrev_b32_e32 v134, 16, v222
	v_and_b32_e32 v222, 0xffff0000, v222
	v_lshlrev_b32_e32 v135, 16, v223
	v_and_b32_e32 v223, 0xffff0000, v223
	v_lshlrev_b32_e32 v136, 16, v224
	v_and_b32_e32 v224, 0xffff0000, v224
	v_lshlrev_b32_e32 v137, 16, v225
	v_and_b32_e32 v225, 0xffff0000, v225
	v_lshlrev_b32_e32 v138, 16, v226
	v_and_b32_e32 v226, 0xffff0000, v226
	v_lshlrev_b32_e32 v139, 16, v227
	v_and_b32_e32 v227, 0xffff0000, v227
	v_lshlrev_b32_e32 v140, 16, v228
	v_and_b32_e32 v228, 0xffff0000, v228
	v_lshlrev_b32_e32 v141, 16, v229
	v_and_b32_e32 v229, 0xffff0000, v229
	v_lshlrev_b32_e32 v142, 16, v230
	v_and_b32_e32 v230, 0xffff0000, v230
	v_lshlrev_b32_e32 v143, 16, v231
	v_and_b32_e32 v231, 0xffff0000, v231
	v_lshlrev_b32_e32 v144, 16, v232
	v_and_b32_e32 v232, 0xffff0000, v232
	v_lshlrev_b32_e32 v145, 16, v233
	v_and_b32_e32 v233, 0xffff0000, v233
	v_fma_f32 v140, s59, v140, -v134
	v_fma_f32 v228, s59, v228, -v222
	v_fma_f32 v141, s59, v141, -v135
	v_fma_f32 v229, s59, v229, -v223
	v_fmac_f32_e32 v134, v210, v140
	v_fmac_f32_e32 v222, v211, v228
	v_fmac_f32_e32 v135, v212, v141
	v_fmac_f32_e32 v223, v213, v229
	v_fma_f32 v142, s59, v142, -v136
	v_fma_f32 v230, s59, v230, -v224
	v_fma_f32 v143, s59, v143, -v137
	v_fma_f32 v231, s59, v231, -v225
	v_fmac_f32_e32 v136, v214, v142
	v_fmac_f32_e32 v224, v215, v230
	v_fmac_f32_e32 v137, v216, v143
	v_fmac_f32_e32 v225, v217, v231
	v_fma_f32 v144, s59, v144, -v138
	v_fma_f32 v232, s59, v232, -v226
	v_fma_f32 v145, s59, v145, -v139
	v_fma_f32 v233, s59, v233, -v227
	v_fmac_f32_e32 v138, v218, v144
	v_fmac_f32_e32 v226, v219, v232
	v_fmac_f32_e32 v139, v220, v145
	v_fmac_f32_e32 v227, v221, v233
	v_mul_f32_e32 v148, v198, v136
	v_mul_f32_e32 v149, v199, v224
	v_mul_f32_e32 v150, v200, v137
	v_mul_f32_e32 v151, v201, v225
	v_mul_f32_e32 v176, v148, v148
	v_fmac_f32_e32 v176, v149, v149
	v_fmac_f32_e32 v176, v150, v150
	v_fmac_f32_e32 v176, v151, v151
	s_waitcnt lgkmcnt(2)
	v_add_f32_e32 v18, v194, v18
	v_add_f32_e32 v19, v195, v19
	v_add_f32_e32 v20, v196, v20
	v_add_f32_e32 v21, v197, v21
	v_add_f32_dpp v176, v176, v176 quad_perm:[1,0,3,2] row_mask:0xf bank_mask:0xf bound_ctrl:1
	v_mul_f32_e32 v18, 0xbfb8aa3b, v18
	v_mul_f32_e32 v19, 0xbfb8aa3b, v19
	v_mul_f32_e32 v20, 0xbfb8aa3b, v20
	v_mul_f32_e32 v21, 0xbfb8aa3b, v21
	v_add_f32_dpp v176, v176, v176 quad_perm:[2,3,0,1] row_mask:0xf bank_mask:0xf bound_ctrl:1
	v_exp_f32_e32 v18, v18
	v_exp_f32_e32 v19, v19
	v_exp_f32_e32 v20, v20
	v_exp_f32_e32 v21, v21
	v_add_f32_dpp v176, v176, v176 row_half_mirror row_mask:0xf bank_mask:0xf bound_ctrl:1
	v_add_f32_e32 v18, 1.0, v18
	v_add_f32_e32 v19, 1.0, v19
	v_add_f32_e32 v20, 1.0, v20
	v_add_f32_e32 v21, 1.0, v21
	v_add_f32_dpp v176, v176, v176 row_mirror row_mask:0xf bank_mask:0xf bound_ctrl:1
	v_rcp_f32_e32 v18, v18
	v_rcp_f32_e32 v19, v19
	v_rcp_f32_e32 v20, v20
	v_rcp_f32_e32 v21, v21
	v_sqrt_f32_e32 v176, v176
	v_add_f32_e32 v14, v190, v14
	v_add_f32_e32 v15, v191, v15
	v_add_f32_e32 v16, v192, v16
	v_add_f32_e32 v17, v193, v17
	v_max_f32_e32 v176, 0x2b8cbccc, v176
	v_mul_f32_e32 v14, 0xbfb8aa3b, v14
	v_mul_f32_e32 v15, 0xbfb8aa3b, v15
	v_mul_f32_e32 v16, 0xbfb8aa3b, v16
	v_mul_f32_e32 v17, 0xbfb8aa3b, v17
	v_rcp_f32_e32 v178, v176
	v_exp_f32_e32 v14, v14
	v_exp_f32_e32 v15, v15
	v_exp_f32_e32 v16, v16
	v_exp_f32_e32 v17, v17
	v_add_f32_e32 v14, 1.0, v14
	v_add_f32_e32 v15, 1.0, v15
	v_add_f32_e32 v16, 1.0, v16
	v_add_f32_e32 v17, 1.0, v17
	v_rcp_f32_e32 v14, v14
	v_rcp_f32_e32 v15, v15
	v_rcp_f32_e32 v16, v16
	v_rcp_f32_e32 v17, v17
	v_mul_f32_e32 v14, 0xbf1b4598, v14
	v_mul_f32_e32 v15, 0xbf1b4598, v15
	v_mul_f32_e32 v16, 0xbf1b4598, v16
	v_mul_f32_e32 v17, 0xbf1b4598, v17
	v_mul_f32_e32 v14, 0x3fb8aa3b, v14
	v_mul_f32_e32 v15, 0x3fb8aa3b, v15
	v_mul_f32_e32 v16, 0x3fb8aa3b, v16
	v_mul_f32_e32 v17, 0x3fb8aa3b, v17
	v_exp_f32_e32 v14, v14
	v_exp_f32_e32 v15, v15
	v_exp_f32_e32 v16, v16
	v_exp_f32_e32 v17, v17
	v_add_f32_e32 v152, -1.0, v18
	v_add_f32_e32 v153, -1.0, v19
	v_add_f32_e32 v154, -1.0, v20
	v_add_f32_e32 v155, -1.0, v21
	v_fma_f32 v152, v202, v152, 1.0
	v_fma_f32 v153, v203, v153, 1.0
	v_fma_f32 v154, v204, v154, 1.0
	v_fma_f32 v155, v205, v155, 1.0
	v_mul_f32_e32 v152, v136, v152
	v_mul_f32_e32 v153, v224, v153
	v_mul_f32_e32 v154, v137, v154
	v_mul_f32_e32 v155, v225, v155
	v_mul_f32_e32 v156, v134, v152
	v_mul_f32_e32 v157, v222, v153
	v_mul_f32_e32 v158, v135, v154
	v_mul_f32_e32 v159, v223, v155
	v_mul_f32_e32 v177, v206, v156
	v_fmac_f32_e32 v177, v207, v157
	v_fmac_f32_e32 v177, v208, v158
	v_fmac_f32_e32 v177, v209, v159
	v_mul_f32_e32 v148, v148, v178
	v_mul_f32_e32 v149, v149, v178
	v_add_f32_dpp v177, v177, v177 quad_perm:[1,0,3,2] row_mask:0xf bank_mask:0xf bound_ctrl:1
	v_mul_f32_e32 v150, v150, v178
	v_mul_f32_e32 v151, v151, v178
	v_add_f32_dpp v177, v177, v177 quad_perm:[2,3,0,1] row_mask:0xf bank_mask:0xf bound_ctrl:1
	v_mul_f32_e32 v18, v18, v148
	v_mul_f32_e32 v19, v19, v149
	v_add_f32_dpp v177, v177, v177 row_half_mirror row_mask:0xf bank_mask:0xf bound_ctrl:1
	v_mul_f32_e32 v20, v20, v150
	v_mul_f32_e32 v21, v21, v151
	v_add_f32_dpp v177, v177, v177 row_mirror row_mask:0xf bank_mask:0xf bound_ctrl:1
	s_lshl_b32 s0, s56, 9
	s_add_u32 s62, s34, s0
	s_addc_u32 s63, s35, 0
	v_mul_f32_e32 v156, v138, v177
	v_mul_f32_e32 v157, v226, v177
	v_mul_f32_e32 v158, v139, v177
	v_mul_f32_e32 v159, v227, v177
	v_cvt_pk_bf16_f32 v72, v134, v222
	v_cvt_pk_bf16_f32 v73, v135, v223
	global_store_dwordx2 v250, v[72:73], s[62:63]
	v_cvt_pk_bf16_f32 v74, v14, v15
	v_cvt_pk_bf16_f32 v75, v16, v17
	s_add_u32 s0, s62, 0x500000
	s_addc_u32 s1, s63, 0
	global_store_dwordx2 v250, v[74:75], s[0:1]
	v_cvt_pk_bf16_f32 v180, v152, v153
	v_cvt_pk_bf16_f32 v181, v154, v155
	s_add_u32 s0, s62, 0xa00000
	s_addc_u32 s1, s63, 0
	global_store_dwordx2 v250, v[180:181], s[0:1]
	v_cvt_pk_bf16_f32 v72, v138, v226
	v_cvt_pk_bf16_f32 v73, v139, v227
	s_add_u32 s0, s62, 0xf00000
	s_addc_u32 s1, s63, 0
	global_store_dwordx2 v250, v[72:73], s[0:1]
	v_cvt_pk_bf16_f32 v74, v148, v149
	v_cvt_pk_bf16_f32 v75, v150, v151
	s_add_u32 s0, s62, 0x1400000
	s_addc_u32 s1, s63, 0
	global_store_dwordx2 v250, v[74:75], s[0:1]
	v_cvt_pk_bf16_f32 v180, v18, v19
	v_cvt_pk_bf16_f32 v181, v20, v21
	s_add_u32 s0, s62, 0x1900000
	s_addc_u32 s1, s63, 0
	global_store_dwordx2 v250, v[180:181], s[0:1]
	v_cvt_pk_bf16_f32 v72, v156, v157
	v_cvt_pk_bf16_f32 v73, v158, v159
	s_lshl_b32 s0, s56, 9
	s_add_u32 s0, s42, s0
	s_addc_u32 s1, s43, 0
	global_store_dwordx2 v250, v[72:73], s[0:1]
	s_add_i32 s56, s53, 3
	s_cmpk_lt_i32 s56, 0x2000
	s_movk_i32 s0, 0x3ff
	s_cselect_b32 s0, 0xff, s0
	s_and_b32 s1, s56, s0
	s_cmp_lg_u32 s1, 0
	s_cselect_b32 s59, 1.0, 0
	s_cselect_b32 s1, -1, 0
	s_add_i32 s1, s56, s1
	s_mul_i32 s0, s56, 0x1d00
	s_add_u32 s76, s28, s0
	s_addc_u32 s77, s29, 0
	s_mul_i32 s0, s1, 0x1d00
	s_add_u32 s78, s28, s0
	s_addc_u32 s79, s29, 0
	global_load_dwordx2 v[222:223], v250, s[76:77] offset:0
	global_load_dwordx2 v[224:225], v250, s[76:77] offset:512
	global_load_dwordx2 v[226:227], v250, s[76:77] offset:1024
	ds_read_b128 v[14:17], v31 offset:2048
	ds_read_b128 v[18:21], v31 offset:22528
	s_waitcnt vmcnt(13)
	v_mov_b32_e32 v228, v236
	v_mov_b32_e32 v229, v237
	v_mov_b32_e32 v230, v238
	v_mov_b32_e32 v231, v239
	v_mov_b32_e32 v232, v240
	v_mov_b32_e32 v233, v241
	v_lshlrev_b32_e32 v134, 16, v236
	v_and_b32_e32 v236, 0xffff0000, v236
	v_lshlrev_b32_e32 v135, 16, v237
	v_and_b32_e32 v237, 0xffff0000, v237
	v_lshlrev_b32_e32 v136, 16, v238
	v_and_b32_e32 v238, 0xffff0000, v238
	v_lshlrev_b32_e32 v137, 16, v239
	v_and_b32_e32 v239, 0xffff0000, v239
	v_lshlrev_b32_e32 v138, 16, v240
	v_and_b32_e32 v240, 0xffff0000, v240
	v_lshlrev_b32_e32 v139, 16, v241
	v_and_b32_e32 v241, 0xffff0000, v241
	v_lshlrev_b32_e32 v140, 16, v242
	v_and_b32_e32 v242, 0xffff0000, v242
	v_lshlrev_b32_e32 v141, 16, v243
	v_and_b32_e32 v243, 0xffff0000, v243
	v_lshlrev_b32_e32 v142, 16, v244
	v_and_b32_e32 v244, 0xffff0000, v244
	v_lshlrev_b32_e32 v143, 16, v245
	v_and_b32_e32 v245, 0xffff0000, v245
	v_lshlrev_b32_e32 v144, 16, v246
	v_and_b32_e32 v246, 0xffff0000, v246
	v_lshlrev_b32_e32 v145, 16, v247
	v_and_b32_e32 v247, 0xffff0000, v247
	v_fma_f32 v140, s60, v140, -v134
	v_fma_f32 v242, s60, v242, -v236
	v_fma_f32 v141, s60, v141, -v135
	v_fma_f32 v243, s60, v243, -v237
	v_fmac_f32_e32 v134, v210, v140
	v_fmac_f32_e32 v236, v211, v242
	v_fmac_f32_e32 v135, v212, v141
	v_fmac_f32_e32 v237, v213, v243
	v_fma_f32 v142, s60, v142, -v136
	v_fma_f32 v244, s60, v244, -v238
	v_fma_f32 v143, s60, v143, -v137
	v_fma_f32 v245, s60, v245, -v239
	v_fmac_f32_e32 v136, v214, v142
	v_fmac_f32_e32 v238, v215, v244
	v_fmac_f32_e32 v137, v216, v143
	v_fmac_f32_e32 v239, v217, v245
	v_fma_f32 v144, s60, v144, -v138
	v_fma_f32 v246, s60, v246, -v240
	v_fma_f32 v145, s60, v145, -v139
	v_fma_f32 v247, s60, v247, -v241
	v_fmac_f32_e32 v138, v218, v144
	v_fmac_f32_e32 v240, v219, v246
	v_fmac_f32_e32 v139, v220, v145
	v_fmac_f32_e32 v241, v221, v247
	v_mul_f32_e32 v148, v198, v136
	v_mul_f32_e32 v149, v199, v238
	v_mul_f32_e32 v150, v200, v137
	v_mul_f32_e32 v151, v201, v239
	v_mul_f32_e32 v176, v148, v148
	v_fmac_f32_e32 v176, v149, v149
	v_fmac_f32_e32 v176, v150, v150
	v_fmac_f32_e32 v176, v151, v151
	s_waitcnt lgkmcnt(2)
	v_add_f32_e32 v26, v194, v26
	v_add_f32_e32 v27, v195, v27
	v_add_f32_e32 v28, v196, v28
	v_add_f32_e32 v29, v197, v29
	v_add_f32_dpp v176, v176, v176 quad_perm:[1,0,3,2] row_mask:0xf bank_mask:0xf bound_ctrl:1
	v_mul_f32_e32 v26, 0xbfb8aa3b, v26
	v_mul_f32_e32 v27, 0xbfb8aa3b, v27
	v_mul_f32_e32 v28, 0xbfb8aa3b, v28
	v_mul_f32_e32 v29, 0xbfb8aa3b, v29
	v_add_f32_dpp v176, v176, v176 quad_perm:[2,3,0,1] row_mask:0xf bank_mask:0xf bound_ctrl:1
	v_exp_f32_e32 v26, v26
	v_exp_f32_e32 v27, v27
	v_exp_f32_e32 v28, v28
	v_exp_f32_e32 v29, v29
	v_add_f32_dpp v176, v176, v176 row_half_mirror row_mask:0xf bank_mask:0xf bound_ctrl:1
	v_add_f32_e32 v26, 1.0, v26
	v_add_f32_e32 v27, 1.0, v27
	v_add_f32_e32 v28, 1.0, v28
	v_add_f32_e32 v29, 1.0, v29
	v_add_f32_dpp v176, v176, v176 row_mirror row_mask:0xf bank_mask:0xf bound_ctrl:1
	v_rcp_f32_e32 v26, v26
	v_rcp_f32_e32 v27, v27
	v_rcp_f32_e32 v28, v28
	v_rcp_f32_e32 v29, v29
	v_sqrt_f32_e32 v176, v176
	v_add_f32_e32 v22, v190, v22
	v_add_f32_e32 v23, v191, v23
	v_add_f32_e32 v24, v192, v24
	v_add_f32_e32 v25, v193, v25
	v_max_f32_e32 v176, 0x2b8cbccc, v176
	v_mul_f32_e32 v22, 0xbfb8aa3b, v22
	v_mul_f32_e32 v23, 0xbfb8aa3b, v23
	v_mul_f32_e32 v24, 0xbfb8aa3b, v24
	v_mul_f32_e32 v25, 0xbfb8aa3b, v25
	v_rcp_f32_e32 v178, v176
	v_exp_f32_e32 v22, v22
	v_exp_f32_e32 v23, v23
	v_exp_f32_e32 v24, v24
	v_exp_f32_e32 v25, v25
	v_add_f32_e32 v22, 1.0, v22
	v_add_f32_e32 v23, 1.0, v23
	v_add_f32_e32 v24, 1.0, v24
	v_add_f32_e32 v25, 1.0, v25
	v_rcp_f32_e32 v22, v22
	v_rcp_f32_e32 v23, v23
	v_rcp_f32_e32 v24, v24
	v_rcp_f32_e32 v25, v25
	v_mul_f32_e32 v22, 0xbf1b4598, v22
	v_mul_f32_e32 v23, 0xbf1b4598, v23
	v_mul_f32_e32 v24, 0xbf1b4598, v24
	v_mul_f32_e32 v25, 0xbf1b4598, v25
	v_mul_f32_e32 v22, 0x3fb8aa3b, v22
	v_mul_f32_e32 v23, 0x3fb8aa3b, v23
	v_mul_f32_e32 v24, 0x3fb8aa3b, v24
	v_mul_f32_e32 v25, 0x3fb8aa3b, v25
	v_exp_f32_e32 v22, v22
	v_exp_f32_e32 v23, v23
	v_exp_f32_e32 v24, v24
	v_exp_f32_e32 v25, v25
	v_add_f32_e32 v152, -1.0, v26
	v_add_f32_e32 v153, -1.0, v27
	v_add_f32_e32 v154, -1.0, v28
	v_add_f32_e32 v155, -1.0, v29
	v_fma_f32 v152, v202, v152, 1.0
	v_fma_f32 v153, v203, v153, 1.0
	v_fma_f32 v154, v204, v154, 1.0
	v_fma_f32 v155, v205, v155, 1.0
	v_mul_f32_e32 v152, v136, v152
	v_mul_f32_e32 v153, v238, v153
	v_mul_f32_e32 v154, v137, v154
	v_mul_f32_e32 v155, v239, v155
	v_mul_f32_e32 v156, v134, v152
	v_mul_f32_e32 v157, v236, v153
	v_mul_f32_e32 v158, v135, v154
	v_mul_f32_e32 v159, v237, v155
	v_mul_f32_e32 v177, v206, v156
	v_fmac_f32_e32 v177, v207, v157
	v_fmac_f32_e32 v177, v208, v158
	v_fmac_f32_e32 v177, v209, v159
	v_mul_f32_e32 v148, v148, v178
	v_mul_f32_e32 v149, v149, v178
	v_add_f32_dpp v177, v177, v177 quad_perm:[1,0,3,2] row_mask:0xf bank_mask:0xf bound_ctrl:1
	v_mul_f32_e32 v150, v150, v178
	v_mul_f32_e32 v151, v151, v178
	v_add_f32_dpp v177, v177, v177 quad_perm:[2,3,0,1] row_mask:0xf bank_mask:0xf bound_ctrl:1
	v_mul_f32_e32 v26, v26, v148
	v_mul_f32_e32 v27, v27, v149
	v_add_f32_dpp v177, v177, v177 row_half_mirror row_mask:0xf bank_mask:0xf bound_ctrl:1
	v_mul_f32_e32 v28, v28, v150
	v_mul_f32_e32 v29, v29, v151
	v_add_f32_dpp v177, v177, v177 row_mirror row_mask:0xf bank_mask:0xf bound_ctrl:1
	s_lshl_b32 s0, s57, 9
	s_add_u32 s62, s34, s0
	s_addc_u32 s63, s35, 0
	v_mul_f32_e32 v156, v138, v177
	v_mul_f32_e32 v157, v240, v177
	v_mul_f32_e32 v158, v139, v177
	v_mul_f32_e32 v159, v241, v177
	v_cvt_pk_bf16_f32 v72, v134, v236
	v_cvt_pk_bf16_f32 v73, v135, v237
	global_store_dwordx2 v250, v[72:73], s[62:63]
	v_cvt_pk_bf16_f32 v74, v22, v23
	v_cvt_pk_bf16_f32 v75, v24, v25
	s_add_u32 s0, s62, 0x500000
	s_addc_u32 s1, s63, 0
	global_store_dwordx2 v250, v[74:75], s[0:1]
	v_cvt_pk_bf16_f32 v180, v152, v153
	v_cvt_pk_bf16_f32 v181, v154, v155
	s_add_u32 s0, s62, 0xa00000
	s_addc_u32 s1, s63, 0
	global_store_dwordx2 v250, v[180:181], s[0:1]
	v_cvt_pk_bf16_f32 v72, v138, v240
	v_cvt_pk_bf16_f32 v73, v139, v241
	s_add_u32 s0, s62, 0xf00000
	s_addc_u32 s1, s63, 0
	global_store_dwordx2 v250, v[72:73], s[0:1]
	v_cvt_pk_bf16_f32 v74, v148, v149
	v_cvt_pk_bf16_f32 v75, v150, v151
	s_add_u32 s0, s62, 0x1400000
	s_addc_u32 s1, s63, 0
	global_store_dwordx2 v250, v[74:75], s[0:1]
	v_cvt_pk_bf16_f32 v180, v26, v27
	v_cvt_pk_bf16_f32 v181, v28, v29
	s_add_u32 s0, s62, 0x1900000
	s_addc_u32 s1, s63, 0
	global_store_dwordx2 v250, v[180:181], s[0:1]
	v_cvt_pk_bf16_f32 v72, v156, v157
	v_cvt_pk_bf16_f32 v73, v158, v159
	s_lshl_b32 s0, s57, 9
	s_add_u32 s0, s42, s0
	s_addc_u32 s1, s43, 0
	global_store_dwordx2 v250, v[72:73], s[0:1]
	s_add_i32 s57, s53, 4
	s_cmpk_lt_i32 s57, 0x2000
	s_movk_i32 s0, 0x3ff
	s_cselect_b32 s0, 0xff, s0
	s_and_b32 s1, s57, s0
	s_cmp_lg_u32 s1, 0
	s_cselect_b32 s60, 1.0, 0
	s_cselect_b32 s1, -1, 0
	s_add_i32 s1, s57, s1
	s_mul_i32 s0, s57, 0x1d00
	s_add_u32 s80, s28, s0
	s_addc_u32 s81, s29, 0
	s_mul_i32 s0, s1, 0x1d00
	s_add_u32 s82, s28, s0
	s_addc_u32 s83, s29, 0
	global_load_dwordx2 v[236:237], v250, s[80:81] offset:0
	global_load_dwordx2 v[238:239], v250, s[80:81] offset:512
	global_load_dwordx2 v[240:241], v250, s[80:81] offset:1024
	ds_read_b128 v[22:25], v31 offset:3072
	ds_read_b128 v[26:29], v31 offset:23552
	s_waitcnt vmcnt(20)
	v_mov_b32_e32 v242, v0
	v_mov_b32_e32 v243, v1
	v_mov_b32_e32 v244, v2
	v_mov_b32_e32 v245, v3
	v_mov_b32_e32 v246, v4
	v_mov_b32_e32 v247, v5
	v_lshlrev_b32_e32 v134, 16, v0
	v_and_b32_e32 v0, 0xffff0000, v0
	v_lshlrev_b32_e32 v135, 16, v1
	v_and_b32_e32 v1, 0xffff0000, v1
	v_lshlrev_b32_e32 v136, 16, v2
	v_and_b32_e32 v2, 0xffff0000, v2
	v_lshlrev_b32_e32 v137, 16, v3
	v_and_b32_e32 v3, 0xffff0000, v3
	v_lshlrev_b32_e32 v138, 16, v4
	v_and_b32_e32 v4, 0xffff0000, v4
	v_lshlrev_b32_e32 v139, 16, v5
	v_and_b32_e32 v5, 0xffff0000, v5
	v_lshlrev_b32_e32 v140, 16, v228
	v_and_b32_e32 v228, 0xffff0000, v228
	v_lshlrev_b32_e32 v141, 16, v229
	v_and_b32_e32 v229, 0xffff0000, v229
	v_lshlrev_b32_e32 v142, 16, v230
	v_and_b32_e32 v230, 0xffff0000, v230
	v_lshlrev_b32_e32 v143, 16, v231
	v_and_b32_e32 v231, 0xffff0000, v231
	v_lshlrev_b32_e32 v144, 16, v232
	v_and_b32_e32 v232, 0xffff0000, v232
	v_lshlrev_b32_e32 v145, 16, v233
	v_and_b32_e32 v233, 0xffff0000, v233
	v_fma_f32 v140, s61, v140, -v134
	v_fma_f32 v228, s61, v228, -v0
	v_fma_f32 v141, s61, v141, -v135
	v_fma_f32 v229, s61, v229, -v1
	v_fmac_f32_e32 v134, v210, v140
	v_fmac_f32_e32 v0, v211, v228
	v_fmac_f32_e32 v135, v212, v141
	v_fmac_f32_e32 v1, v213, v229
	v_fma_f32 v142, s61, v142, -v136
	v_fma_f32 v230, s61, v230, -v2
	v_fma_f32 v143, s61, v143, -v137
	v_fma_f32 v231, s61, v231, -v3
	v_fmac_f32_e32 v136, v214, v142
	v_fmac_f32_e32 v2, v215, v230
	v_fmac_f32_e32 v137, v216, v143
	v_fmac_f32_e32 v3, v217, v231
	v_fma_f32 v144, s61, v144, -v138
	v_fma_f32 v232, s61, v232, -v4
	v_fma_f32 v145, s61, v145, -v139
	v_fma_f32 v233, s61, v233, -v5
	v_fmac_f32_e32 v138, v218, v144
	v_fmac_f32_e32 v4, v219, v232
	v_fmac_f32_e32 v139, v220, v145
	v_fmac_f32_e32 v5, v221, v233
	v_mul_f32_e32 v148, v198, v136
	v_mul_f32_e32 v149, v199, v2
	v_mul_f32_e32 v150, v200, v137
	v_mul_f32_e32 v151, v201, v3
	v_mul_f32_e32 v176, v148, v148
	v_fmac_f32_e32 v176, v149, v149
	v_fmac_f32_e32 v176, v150, v150
	v_fmac_f32_e32 v176, v151, v151
	s_waitcnt lgkmcnt(2)
	v_add_f32_e32 v18, v194, v18
	v_add_f32_e32 v19, v195, v19
	v_add_f32_e32 v20, v196, v20
	v_add_f32_e32 v21, v197, v21
	v_add_f32_dpp v176, v176, v176 quad_perm:[1,0,3,2] row_mask:0xf bank_mask:0xf bound_ctrl:1
	v_mul_f32_e32 v18, 0xbfb8aa3b, v18
	v_mul_f32_e32 v19, 0xbfb8aa3b, v19
	v_mul_f32_e32 v20, 0xbfb8aa3b, v20
	v_mul_f32_e32 v21, 0xbfb8aa3b, v21
	v_add_f32_dpp v176, v176, v176 quad_perm:[2,3,0,1] row_mask:0xf bank_mask:0xf bound_ctrl:1
	v_exp_f32_e32 v18, v18
	v_exp_f32_e32 v19, v19
	v_exp_f32_e32 v20, v20
	v_exp_f32_e32 v21, v21
	v_add_f32_dpp v176, v176, v176 row_half_mirror row_mask:0xf bank_mask:0xf bound_ctrl:1
	v_add_f32_e32 v18, 1.0, v18
	v_add_f32_e32 v19, 1.0, v19
	v_add_f32_e32 v20, 1.0, v20
	v_add_f32_e32 v21, 1.0, v21
	v_add_f32_dpp v176, v176, v176 row_mirror row_mask:0xf bank_mask:0xf bound_ctrl:1
	v_rcp_f32_e32 v18, v18
	v_rcp_f32_e32 v19, v19
	v_rcp_f32_e32 v20, v20
	v_rcp_f32_e32 v21, v21
	v_sqrt_f32_e32 v176, v176
	v_add_f32_e32 v14, v190, v14
	v_add_f32_e32 v15, v191, v15
	v_add_f32_e32 v16, v192, v16
	v_add_f32_e32 v17, v193, v17
	v_max_f32_e32 v176, 0x2b8cbccc, v176
	v_mul_f32_e32 v14, 0xbfb8aa3b, v14
	v_mul_f32_e32 v15, 0xbfb8aa3b, v15
	v_mul_f32_e32 v16, 0xbfb8aa3b, v16
	v_mul_f32_e32 v17, 0xbfb8aa3b, v17
	v_rcp_f32_e32 v178, v176
	v_exp_f32_e32 v14, v14
	v_exp_f32_e32 v15, v15
	v_exp_f32_e32 v16, v16
	v_exp_f32_e32 v17, v17
	v_add_f32_e32 v14, 1.0, v14
	v_add_f32_e32 v15, 1.0, v15
	v_add_f32_e32 v16, 1.0, v16
	v_add_f32_e32 v17, 1.0, v17
	v_rcp_f32_e32 v14, v14
	v_rcp_f32_e32 v15, v15
	v_rcp_f32_e32 v16, v16
	v_rcp_f32_e32 v17, v17
	v_mul_f32_e32 v14, 0xbf1b4598, v14
	v_mul_f32_e32 v15, 0xbf1b4598, v15
	v_mul_f32_e32 v16, 0xbf1b4598, v16
	v_mul_f32_e32 v17, 0xbf1b4598, v17
	v_mul_f32_e32 v14, 0x3fb8aa3b, v14
	v_mul_f32_e32 v15, 0x3fb8aa3b, v15
	v_mul_f32_e32 v16, 0x3fb8aa3b, v16
	v_mul_f32_e32 v17, 0x3fb8aa3b, v17
	v_exp_f32_e32 v14, v14
	v_exp_f32_e32 v15, v15
	v_exp_f32_e32 v16, v16
	v_exp_f32_e32 v17, v17
	v_add_f32_e32 v152, -1.0, v18
	v_add_f32_e32 v153, -1.0, v19
	v_add_f32_e32 v154, -1.0, v20
	v_add_f32_e32 v155, -1.0, v21
	v_fma_f32 v152, v202, v152, 1.0
	v_fma_f32 v153, v203, v153, 1.0
	v_fma_f32 v154, v204, v154, 1.0
	v_fma_f32 v155, v205, v155, 1.0
	v_mul_f32_e32 v152, v136, v152
	v_mul_f32_e32 v153, v2, v153
	v_mul_f32_e32 v154, v137, v154
	v_mul_f32_e32 v155, v3, v155
	v_mul_f32_e32 v156, v134, v152
	v_mul_f32_e32 v157, v0, v153
	v_mul_f32_e32 v158, v135, v154
	v_mul_f32_e32 v159, v1, v155
	v_mul_f32_e32 v177, v206, v156
	v_fmac_f32_e32 v177, v207, v157
	v_fmac_f32_e32 v177, v208, v158
	v_fmac_f32_e32 v177, v209, v159
	v_mul_f32_e32 v148, v148, v178
	v_mul_f32_e32 v149, v149, v178
	v_add_f32_dpp v177, v177, v177 quad_perm:[1,0,3,2] row_mask:0xf bank_mask:0xf bound_ctrl:1
	v_mul_f32_e32 v150, v150, v178
	v_mul_f32_e32 v151, v151, v178
	v_add_f32_dpp v177, v177, v177 quad_perm:[2,3,0,1] row_mask:0xf bank_mask:0xf bound_ctrl:1
	v_mul_f32_e32 v18, v18, v148
	v_mul_f32_e32 v19, v19, v149
	v_add_f32_dpp v177, v177, v177 row_half_mirror row_mask:0xf bank_mask:0xf bound_ctrl:1
	v_mul_f32_e32 v20, v20, v150
	v_mul_f32_e32 v21, v21, v151
	v_add_f32_dpp v177, v177, v177 row_mirror row_mask:0xf bank_mask:0xf bound_ctrl:1
	s_lshl_b32 s0, s58, 9
	s_add_u32 s62, s34, s0
	s_addc_u32 s63, s35, 0
	v_mul_f32_e32 v156, v138, v177
	v_mul_f32_e32 v157, v4, v177
	v_mul_f32_e32 v158, v139, v177
	v_mul_f32_e32 v159, v5, v177
	v_cvt_pk_bf16_f32 v72, v134, v0
	v_cvt_pk_bf16_f32 v73, v135, v1
	global_store_dwordx2 v250, v[72:73], s[62:63]
	v_cvt_pk_bf16_f32 v74, v14, v15
	v_cvt_pk_bf16_f32 v75, v16, v17
	s_add_u32 s0, s62, 0x500000
	s_addc_u32 s1, s63, 0
	global_store_dwordx2 v250, v[74:75], s[0:1]
	v_cvt_pk_bf16_f32 v180, v152, v153
	v_cvt_pk_bf16_f32 v181, v154, v155
	s_add_u32 s0, s62, 0xa00000
	s_addc_u32 s1, s63, 0
	global_store_dwordx2 v250, v[180:181], s[0:1]
	v_cvt_pk_bf16_f32 v72, v138, v4
	v_cvt_pk_bf16_f32 v73, v139, v5
	s_add_u32 s0, s62, 0xf00000
	s_addc_u32 s1, s63, 0
	global_store_dwordx2 v250, v[72:73], s[0:1]
	v_cvt_pk_bf16_f32 v74, v148, v149
	v_cvt_pk_bf16_f32 v75, v150, v151
	s_add_u32 s0, s62, 0x1400000
	s_addc_u32 s1, s63, 0
	global_store_dwordx2 v250, v[74:75], s[0:1]
	v_cvt_pk_bf16_f32 v180, v18, v19
	v_cvt_pk_bf16_f32 v181, v20, v21
	s_add_u32 s0, s62, 0x1900000
	s_addc_u32 s1, s63, 0
	global_store_dwordx2 v250, v[180:181], s[0:1]
	v_cvt_pk_bf16_f32 v72, v156, v157
	v_cvt_pk_bf16_f32 v73, v158, v159
	s_lshl_b32 s0, s58, 9
	s_add_u32 s0, s42, s0
	s_addc_u32 s1, s43, 0
	global_store_dwordx2 v250, v[72:73], s[0:1]
	ds_read_b128 v[14:17], v31 offset:4096
	ds_read_b128 v[18:21], v31 offset:24576
	s_waitcnt vmcnt(17)
	v_mov_b32_e32 v228, v222
	v_mov_b32_e32 v229, v223
	v_mov_b32_e32 v230, v224
	v_mov_b32_e32 v231, v225
	v_mov_b32_e32 v232, v226
	v_mov_b32_e32 v233, v227
	v_lshlrev_b32_e32 v134, 16, v222
	v_and_b32_e32 v222, 0xffff0000, v222
	v_lshlrev_b32_e32 v135, 16, v223
	v_and_b32_e32 v223, 0xffff0000, v223
	v_lshlrev_b32_e32 v136, 16, v224
	v_and_b32_e32 v224, 0xffff0000, v224
	v_lshlrev_b32_e32 v137, 16, v225
	v_and_b32_e32 v225, 0xffff0000, v225
	v_lshlrev_b32_e32 v138, 16, v226
	v_and_b32_e32 v226, 0xffff0000, v226
	v_lshlrev_b32_e32 v139, 16, v227
	v_and_b32_e32 v227, 0xffff0000, v227
	v_lshlrev_b32_e32 v140, 16, v242
	v_and_b32_e32 v242, 0xffff0000, v242
	v_lshlrev_b32_e32 v141, 16, v243
	v_and_b32_e32 v243, 0xffff0000, v243
	v_lshlrev_b32_e32 v142, 16, v244
	v_and_b32_e32 v244, 0xffff0000, v244
	v_lshlrev_b32_e32 v143, 16, v245
	v_and_b32_e32 v245, 0xffff0000, v245
	v_lshlrev_b32_e32 v144, 16, v246
	v_and_b32_e32 v246, 0xffff0000, v246
	v_lshlrev_b32_e32 v145, 16, v247
	v_and_b32_e32 v247, 0xffff0000, v247
	v_fma_f32 v140, s59, v140, -v134
	v_fma_f32 v242, s59, v242, -v222
	v_fma_f32 v141, s59, v141, -v135
	v_fma_f32 v243, s59, v243, -v223
	v_fmac_f32_e32 v134, v210, v140
	v_fmac_f32_e32 v222, v211, v242
	v_fmac_f32_e32 v135, v212, v141
	v_fmac_f32_e32 v223, v213, v243
	v_fma_f32 v142, s59, v142, -v136
	v_fma_f32 v244, s59, v244, -v224
	v_fma_f32 v143, s59, v143, -v137
	v_fma_f32 v245, s59, v245, -v225
	v_fmac_f32_e32 v136, v214, v142
	v_fmac_f32_e32 v224, v215, v244
	v_fmac_f32_e32 v137, v216, v143
	v_fmac_f32_e32 v225, v217, v245
	v_fma_f32 v144, s59, v144, -v138
	v_fma_f32 v246, s59, v246, -v226
	v_fma_f32 v145, s59, v145, -v139
	v_fma_f32 v247, s59, v247, -v227
	v_fmac_f32_e32 v138, v218, v144
	v_fmac_f32_e32 v226, v219, v246
	v_fmac_f32_e32 v139, v220, v145
	v_fmac_f32_e32 v227, v221, v247
	v_mul_f32_e32 v148, v198, v136
	v_mul_f32_e32 v149, v199, v224
	v_mul_f32_e32 v150, v200, v137
	v_mul_f32_e32 v151, v201, v225
	v_mul_f32_e32 v176, v148, v148
	v_fmac_f32_e32 v176, v149, v149
	v_fmac_f32_e32 v176, v150, v150
	v_fmac_f32_e32 v176, v151, v151
	s_waitcnt lgkmcnt(2)
	v_add_f32_e32 v26, v194, v26
	v_add_f32_e32 v27, v195, v27
	v_add_f32_e32 v28, v196, v28
	v_add_f32_e32 v29, v197, v29
	v_add_f32_dpp v176, v176, v176 quad_perm:[1,0,3,2] row_mask:0xf bank_mask:0xf bound_ctrl:1
	v_mul_f32_e32 v26, 0xbfb8aa3b, v26
	v_mul_f32_e32 v27, 0xbfb8aa3b, v27
	v_mul_f32_e32 v28, 0xbfb8aa3b, v28
	v_mul_f32_e32 v29, 0xbfb8aa3b, v29
	v_add_f32_dpp v176, v176, v176 quad_perm:[2,3,0,1] row_mask:0xf bank_mask:0xf bound_ctrl:1
	v_exp_f32_e32 v26, v26
	v_exp_f32_e32 v27, v27
	v_exp_f32_e32 v28, v28
	v_exp_f32_e32 v29, v29
	v_add_f32_dpp v176, v176, v176 row_half_mirror row_mask:0xf bank_mask:0xf bound_ctrl:1
	v_add_f32_e32 v26, 1.0, v26
	v_add_f32_e32 v27, 1.0, v27
	v_add_f32_e32 v28, 1.0, v28
	v_add_f32_e32 v29, 1.0, v29
	v_add_f32_dpp v176, v176, v176 row_mirror row_mask:0xf bank_mask:0xf bound_ctrl:1
	v_rcp_f32_e32 v26, v26
	v_rcp_f32_e32 v27, v27
	v_rcp_f32_e32 v28, v28
	v_rcp_f32_e32 v29, v29
	v_sqrt_f32_e32 v176, v176
	v_add_f32_e32 v22, v190, v22
	v_add_f32_e32 v23, v191, v23
	v_add_f32_e32 v24, v192, v24
	v_add_f32_e32 v25, v193, v25
	v_max_f32_e32 v176, 0x2b8cbccc, v176
	v_mul_f32_e32 v22, 0xbfb8aa3b, v22
	v_mul_f32_e32 v23, 0xbfb8aa3b, v23
	v_mul_f32_e32 v24, 0xbfb8aa3b, v24
	v_mul_f32_e32 v25, 0xbfb8aa3b, v25
	v_rcp_f32_e32 v178, v176
	v_exp_f32_e32 v22, v22
	v_exp_f32_e32 v23, v23
	v_exp_f32_e32 v24, v24
	v_exp_f32_e32 v25, v25
	v_add_f32_e32 v22, 1.0, v22
	v_add_f32_e32 v23, 1.0, v23
	v_add_f32_e32 v24, 1.0, v24
	v_add_f32_e32 v25, 1.0, v25
	v_rcp_f32_e32 v22, v22
	v_rcp_f32_e32 v23, v23
	v_rcp_f32_e32 v24, v24
	v_rcp_f32_e32 v25, v25
	v_mul_f32_e32 v22, 0xbf1b4598, v22
	v_mul_f32_e32 v23, 0xbf1b4598, v23
	v_mul_f32_e32 v24, 0xbf1b4598, v24
	v_mul_f32_e32 v25, 0xbf1b4598, v25
	v_mul_f32_e32 v22, 0x3fb8aa3b, v22
	v_mul_f32_e32 v23, 0x3fb8aa3b, v23
	v_mul_f32_e32 v24, 0x3fb8aa3b, v24
	v_mul_f32_e32 v25, 0x3fb8aa3b, v25
	v_exp_f32_e32 v22, v22
	v_exp_f32_e32 v23, v23
	v_exp_f32_e32 v24, v24
	v_exp_f32_e32 v25, v25
	v_add_f32_e32 v152, -1.0, v26
	v_add_f32_e32 v153, -1.0, v27
	v_add_f32_e32 v154, -1.0, v28
	v_add_f32_e32 v155, -1.0, v29
	v_fma_f32 v152, v202, v152, 1.0
	v_fma_f32 v153, v203, v153, 1.0
	v_fma_f32 v154, v204, v154, 1.0
	v_fma_f32 v155, v205, v155, 1.0
	v_mul_f32_e32 v152, v136, v152
	v_mul_f32_e32 v153, v224, v153
	v_mul_f32_e32 v154, v137, v154
	v_mul_f32_e32 v155, v225, v155
	v_mul_f32_e32 v156, v134, v152
	v_mul_f32_e32 v157, v222, v153
	v_mul_f32_e32 v158, v135, v154
	v_mul_f32_e32 v159, v223, v155
	v_mul_f32_e32 v177, v206, v156
	v_fmac_f32_e32 v177, v207, v157
	v_fmac_f32_e32 v177, v208, v158
	v_fmac_f32_e32 v177, v209, v159
	v_mul_f32_e32 v148, v148, v178
	v_mul_f32_e32 v149, v149, v178
	v_add_f32_dpp v177, v177, v177 quad_perm:[1,0,3,2] row_mask:0xf bank_mask:0xf bound_ctrl:1
	v_mul_f32_e32 v150, v150, v178
	v_mul_f32_e32 v151, v151, v178
	v_add_f32_dpp v177, v177, v177 quad_perm:[2,3,0,1] row_mask:0xf bank_mask:0xf bound_ctrl:1
	v_mul_f32_e32 v26, v26, v148
	v_mul_f32_e32 v27, v27, v149
	v_add_f32_dpp v177, v177, v177 row_half_mirror row_mask:0xf bank_mask:0xf bound_ctrl:1
	v_mul_f32_e32 v28, v28, v150
	v_mul_f32_e32 v29, v29, v151
	v_add_f32_dpp v177, v177, v177 row_mirror row_mask:0xf bank_mask:0xf bound_ctrl:1
	s_lshl_b32 s0, s56, 9
	s_add_u32 s62, s34, s0
	s_addc_u32 s63, s35, 0
	v_mul_f32_e32 v156, v138, v177
	v_mul_f32_e32 v157, v226, v177
	v_mul_f32_e32 v158, v139, v177
	v_mul_f32_e32 v159, v227, v177
	v_cvt_pk_bf16_f32 v72, v134, v222
	v_cvt_pk_bf16_f32 v73, v135, v223
	global_store_dwordx2 v250, v[72:73], s[62:63]
	v_cvt_pk_bf16_f32 v74, v22, v23
	v_cvt_pk_bf16_f32 v75, v24, v25
	s_add_u32 s0, s62, 0x500000
	s_addc_u32 s1, s63, 0
	global_store_dwordx2 v250, v[74:75], s[0:1]
	v_cvt_pk_bf16_f32 v180, v152, v153
	v_cvt_pk_bf16_f32 v181, v154, v155
	s_add_u32 s0, s62, 0xa00000
	s_addc_u32 s1, s63, 0
	global_store_dwordx2 v250, v[180:181], s[0:1]
	v_cvt_pk_bf16_f32 v72, v138, v226
	v_cvt_pk_bf16_f32 v73, v139, v227
	s_add_u32 s0, s62, 0xf00000
	s_addc_u32 s1, s63, 0
	global_store_dwordx2 v250, v[72:73], s[0:1]
	v_cvt_pk_bf16_f32 v74, v148, v149
	v_cvt_pk_bf16_f32 v75, v150, v151
	s_add_u32 s0, s62, 0x1400000
	s_addc_u32 s1, s63, 0
	global_store_dwordx2 v250, v[74:75], s[0:1]
	v_cvt_pk_bf16_f32 v180, v26, v27
	v_cvt_pk_bf16_f32 v181, v28, v29
	s_add_u32 s0, s62, 0x1900000
	s_addc_u32 s1, s63, 0
	global_store_dwordx2 v250, v[180:181], s[0:1]
	v_cvt_pk_bf16_f32 v72, v156, v157
	v_cvt_pk_bf16_f32 v73, v158, v159
	s_lshl_b32 s0, s56, 9
	s_add_u32 s0, s42, s0
	s_addc_u32 s1, s43, 0
	global_store_dwordx2 v250, v[72:73], s[0:1]
	s_waitcnt vmcnt(14)
	v_lshlrev_b32_e32 v134, 16, v236
	v_and_b32_e32 v236, 0xffff0000, v236
	v_lshlrev_b32_e32 v135, 16, v237
	v_and_b32_e32 v237, 0xffff0000, v237
	v_lshlrev_b32_e32 v136, 16, v238
	v_and_b32_e32 v238, 0xffff0000, v238
	v_lshlrev_b32_e32 v137, 16, v239
	v_and_b32_e32 v239, 0xffff0000, v239
	v_lshlrev_b32_e32 v138, 16, v240
	v_and_b32_e32 v240, 0xffff0000, v240
	v_lshlrev_b32_e32 v139, 16, v241
	v_and_b32_e32 v241, 0xffff0000, v241
	v_lshlrev_b32_e32 v140, 16, v228
	v_and_b32_e32 v228, 0xffff0000, v228
	v_lshlrev_b32_e32 v141, 16, v229
	v_and_b32_e32 v229, 0xffff0000, v229
	v_lshlrev_b32_e32 v142, 16, v230
	v_and_b32_e32 v230, 0xffff0000, v230
	v_lshlrev_b32_e32 v143, 16, v231
	v_and_b32_e32 v231, 0xffff0000, v231
	v_lshlrev_b32_e32 v144, 16, v232
	v_and_b32_e32 v232, 0xffff0000, v232
	v_lshlrev_b32_e32 v145, 16, v233
	v_and_b32_e32 v233, 0xffff0000, v233
	v_fma_f32 v140, s60, v140, -v134
	v_fma_f32 v228, s60, v228, -v236
	v_fma_f32 v141, s60, v141, -v135
	v_fma_f32 v229, s60, v229, -v237
	v_fmac_f32_e32 v134, v210, v140
	v_fmac_f32_e32 v236, v211, v228
	v_fmac_f32_e32 v135, v212, v141
	v_fmac_f32_e32 v237, v213, v229
	v_fma_f32 v142, s60, v142, -v136
	v_fma_f32 v230, s60, v230, -v238
	v_fma_f32 v143, s60, v143, -v137
	v_fma_f32 v231, s60, v231, -v239
	v_fmac_f32_e32 v136, v214, v142
	v_fmac_f32_e32 v238, v215, v230
	v_fmac_f32_e32 v137, v216, v143
	v_fmac_f32_e32 v239, v217, v231
	v_fma_f32 v144, s60, v144, -v138
	v_fma_f32 v232, s60, v232, -v240
	v_fma_f32 v145, s60, v145, -v139
	v_fma_f32 v233, s60, v233, -v241
	v_fmac_f32_e32 v138, v218, v144
	v_fmac_f32_e32 v240, v219, v232
	v_fmac_f32_e32 v139, v220, v145
	v_fmac_f32_e32 v241, v221, v233
	v_mul_f32_e32 v148, v198, v136
	v_mul_f32_e32 v149, v199, v238
	v_mul_f32_e32 v150, v200, v137
	v_mul_f32_e32 v151, v201, v239
	v_mul_f32_e32 v176, v148, v148
	v_fmac_f32_e32 v176, v149, v149
	v_fmac_f32_e32 v176, v150, v150
	v_fmac_f32_e32 v176, v151, v151
	s_waitcnt lgkmcnt(0)
	v_add_f32_e32 v18, v194, v18
	v_add_f32_e32 v19, v195, v19
	v_add_f32_e32 v20, v196, v20
	v_add_f32_e32 v21, v197, v21
	v_add_f32_dpp v176, v176, v176 quad_perm:[1,0,3,2] row_mask:0xf bank_mask:0xf bound_ctrl:1
	v_mul_f32_e32 v18, 0xbfb8aa3b, v18
	v_mul_f32_e32 v19, 0xbfb8aa3b, v19
	v_mul_f32_e32 v20, 0xbfb8aa3b, v20
	v_mul_f32_e32 v21, 0xbfb8aa3b, v21
	v_add_f32_dpp v176, v176, v176 quad_perm:[2,3,0,1] row_mask:0xf bank_mask:0xf bound_ctrl:1
	v_exp_f32_e32 v18, v18
	v_exp_f32_e32 v19, v19
	v_exp_f32_e32 v20, v20
	v_exp_f32_e32 v21, v21
	v_add_f32_dpp v176, v176, v176 row_half_mirror row_mask:0xf bank_mask:0xf bound_ctrl:1
	v_add_f32_e32 v18, 1.0, v18
	v_add_f32_e32 v19, 1.0, v19
	v_add_f32_e32 v20, 1.0, v20
	v_add_f32_e32 v21, 1.0, v21
	v_add_f32_dpp v176, v176, v176 row_mirror row_mask:0xf bank_mask:0xf bound_ctrl:1
	v_rcp_f32_e32 v18, v18
	v_rcp_f32_e32 v19, v19
	v_rcp_f32_e32 v20, v20
	v_rcp_f32_e32 v21, v21
	v_sqrt_f32_e32 v176, v176
	v_add_f32_e32 v14, v190, v14
	v_add_f32_e32 v15, v191, v15
	v_add_f32_e32 v16, v192, v16
	v_add_f32_e32 v17, v193, v17
	v_max_f32_e32 v176, 0x2b8cbccc, v176
	v_mul_f32_e32 v14, 0xbfb8aa3b, v14
	v_mul_f32_e32 v15, 0xbfb8aa3b, v15
	v_mul_f32_e32 v16, 0xbfb8aa3b, v16
	v_mul_f32_e32 v17, 0xbfb8aa3b, v17
	v_rcp_f32_e32 v178, v176
	v_exp_f32_e32 v14, v14
	v_exp_f32_e32 v15, v15
	v_exp_f32_e32 v16, v16
	v_exp_f32_e32 v17, v17
	v_add_f32_e32 v14, 1.0, v14
	v_add_f32_e32 v15, 1.0, v15
	v_add_f32_e32 v16, 1.0, v16
	v_add_f32_e32 v17, 1.0, v17
	v_rcp_f32_e32 v14, v14
	v_rcp_f32_e32 v15, v15
	v_rcp_f32_e32 v16, v16
	v_rcp_f32_e32 v17, v17
	v_mul_f32_e32 v14, 0xbf1b4598, v14
	v_mul_f32_e32 v15, 0xbf1b4598, v15
	v_mul_f32_e32 v16, 0xbf1b4598, v16
	v_mul_f32_e32 v17, 0xbf1b4598, v17
	v_mul_f32_e32 v14, 0x3fb8aa3b, v14
	v_mul_f32_e32 v15, 0x3fb8aa3b, v15
	v_mul_f32_e32 v16, 0x3fb8aa3b, v16
	v_mul_f32_e32 v17, 0x3fb8aa3b, v17
	v_exp_f32_e32 v14, v14
	v_exp_f32_e32 v15, v15
	v_exp_f32_e32 v16, v16
	v_exp_f32_e32 v17, v17
	v_add_f32_e32 v152, -1.0, v18
	v_add_f32_e32 v153, -1.0, v19
	v_add_f32_e32 v154, -1.0, v20
	v_add_f32_e32 v155, -1.0, v21
	v_fma_f32 v152, v202, v152, 1.0
	v_fma_f32 v153, v203, v153, 1.0
	v_fma_f32 v154, v204, v154, 1.0
	v_fma_f32 v155, v205, v155, 1.0
	v_mul_f32_e32 v152, v136, v152
	v_mul_f32_e32 v153, v238, v153
	v_mul_f32_e32 v154, v137, v154
	v_mul_f32_e32 v155, v239, v155
	v_mul_f32_e32 v156, v134, v152
	v_mul_f32_e32 v157, v236, v153
	v_mul_f32_e32 v158, v135, v154
	v_mul_f32_e32 v159, v237, v155
	v_mul_f32_e32 v177, v206, v156
	v_fmac_f32_e32 v177, v207, v157
	v_fmac_f32_e32 v177, v208, v158
	v_fmac_f32_e32 v177, v209, v159
	v_mul_f32_e32 v148, v148, v178
	v_mul_f32_e32 v149, v149, v178
	v_add_f32_dpp v177, v177, v177 quad_perm:[1,0,3,2] row_mask:0xf bank_mask:0xf bound_ctrl:1
	v_mul_f32_e32 v150, v150, v178
	v_mul_f32_e32 v151, v151, v178
	v_add_f32_dpp v177, v177, v177 quad_perm:[2,3,0,1] row_mask:0xf bank_mask:0xf bound_ctrl:1
	v_mul_f32_e32 v18, v18, v148
	v_mul_f32_e32 v19, v19, v149
	v_add_f32_dpp v177, v177, v177 row_half_mirror row_mask:0xf bank_mask:0xf bound_ctrl:1
	v_mul_f32_e32 v20, v20, v150
	v_mul_f32_e32 v21, v21, v151
	v_add_f32_dpp v177, v177, v177 row_mirror row_mask:0xf bank_mask:0xf bound_ctrl:1
	s_lshl_b32 s0, s57, 9
	s_add_u32 s62, s34, s0
	s_addc_u32 s63, s35, 0
	v_mul_f32_e32 v156, v138, v177
	v_mul_f32_e32 v157, v240, v177
	v_mul_f32_e32 v158, v139, v177
	v_mul_f32_e32 v159, v241, v177
	v_cvt_pk_bf16_f32 v72, v134, v236
	v_cvt_pk_bf16_f32 v73, v135, v237
	global_store_dwordx2 v250, v[72:73], s[62:63]
	v_cvt_pk_bf16_f32 v74, v14, v15
	v_cvt_pk_bf16_f32 v75, v16, v17
	s_add_u32 s0, s62, 0x500000
	s_addc_u32 s1, s63, 0
	global_store_dwordx2 v250, v[74:75], s[0:1]
	v_cvt_pk_bf16_f32 v180, v152, v153
	v_cvt_pk_bf16_f32 v181, v154, v155
	s_add_u32 s0, s62, 0xa00000
	s_addc_u32 s1, s63, 0
	global_store_dwordx2 v250, v[180:181], s[0:1]
	v_cvt_pk_bf16_f32 v72, v138, v240
	v_cvt_pk_bf16_f32 v73, v139, v241
	s_add_u32 s0, s62, 0xf00000
	s_addc_u32 s1, s63, 0
	global_store_dwordx2 v250, v[72:73], s[0:1]
	v_cvt_pk_bf16_f32 v74, v148, v149
	v_cvt_pk_bf16_f32 v75, v150, v151
	s_add_u32 s0, s62, 0x1400000
	s_addc_u32 s1, s63, 0
	global_store_dwordx2 v250, v[74:75], s[0:1]
	v_cvt_pk_bf16_f32 v180, v18, v19
	v_cvt_pk_bf16_f32 v181, v20, v21
	s_add_u32 s0, s62, 0x1900000
	s_addc_u32 s1, s63, 0
	global_store_dwordx2 v250, v[180:181], s[0:1]
	v_cvt_pk_bf16_f32 v72, v156, v157
	v_cvt_pk_bf16_f32 v73, v158, v159
	s_lshl_b32 s0, s57, 9
	s_add_u32 s0, s42, s0
	s_addc_u32 s1, s43, 0
	global_store_dwordx2 v250, v[72:73], s[0:1]
	s_branch .LBB0_476
.Lprep_tok_d1:
	ds_read_b128 v[210:213], v251 offset:53248
	ds_read_b128 v[214:217], v251 offset:54272
	ds_read_b128 v[218:221], v251 offset:55296
	ds_read_b128 v[198:201], v251 offset:56320
	ds_read_b128 v[194:197], v251 offset:57344
	ds_read_b128 v[190:193], v251 offset:58368
	ds_read_b128 v[202:205], v251 offset:59392
	ds_read_b128 v[206:209], v251 offset:60416
	s_add_u32 s34, s34, 0x1e00000
	s_addc_u32 s35, s35, 0
	s_add_i32 s56, s53, 4
	s_cmpk_lt_i32 s56, 0x2000
	s_movk_i32 s0, 0x3ff
	s_cselect_b32 s0, 0xff, s0
	s_and_b32 s1, s56, s0
	s_cmp_lg_u32 s1, s0
	s_cselect_b32 s59, 1.0, 0
	s_cselect_b32 s1, 1, 0
	s_add_i32 s1, s56, s1
	s_mul_i32 s0, s56, 0x1d00
	s_add_u32 s76, s28, s0
	s_addc_u32 s77, s29, 0
	s_mul_i32 s0, s1, 0x1d00
	s_add_u32 s78, s28, s0
	s_addc_u32 s79, s29, 0
	global_load_dwordx2 v[222:223], v250, s[76:77] offset:0
	global_load_dwordx2 v[224:225], v250, s[76:77] offset:512
	global_load_dwordx2 v[226:227], v250, s[76:77] offset:1024
	global_load_dwordx2 v[228:229], v250, s[78:79] offset:0
	global_load_dwordx2 v[230:231], v250, s[78:79] offset:512
	global_load_dwordx2 v[232:233], v250, s[78:79] offset:1024
	s_lshl_b32 s0, s56, 9
	s_add_u32 s0, s42, s0
	s_addc_u32 s1, s43, 0
	global_load_dwordx2 v[234:235], v250, s[0:1]
	s_add_i32 s57, s53, 3
	s_cmpk_lt_i32 s57, 0x2000
	s_movk_i32 s0, 0x3ff
	s_cselect_b32 s0, 0xff, s0
	s_and_b32 s1, s57, s0
	s_cmp_lg_u32 s1, s0
	s_cselect_b32 s60, 1.0, 0
	s_cselect_b32 s1, 1, 0
	s_add_i32 s1, s57, s1
	s_mul_i32 s0, s57, 0x1d00
	s_add_u32 s80, s28, s0
	s_addc_u32 s81, s29, 0
	s_mul_i32 s0, s1, 0x1d00
	s_add_u32 s82, s28, s0
	s_addc_u32 s83, s29, 0
	global_load_dwordx2 v[236:237], v250, s[80:81] offset:0
	global_load_dwordx2 v[238:239], v250, s[80:81] offset:512
	global_load_dwordx2 v[240:241], v250, s[80:81] offset:1024
	s_lshl_b32 s0, s57, 9
	s_add_u32 s0, s42, s0
	s_addc_u32 s1, s43, 0
	global_load_dwordx2 v[248:249], v250, s[0:1]
	s_add_i32 s58, s53, 2
	s_cmpk_lt_i32 s58, 0x2000
	s_movk_i32 s0, 0x3ff
	s_cselect_b32 s0, 0xff, s0
	s_and_b32 s1, s58, s0
	s_cmp_lg_u32 s1, s0
	s_cselect_b32 s61, 1.0, 0
	s_cselect_b32 s1, 1, 0
	s_add_i32 s1, s58, s1
	s_mul_i32 s0, s58, 0x1d00
	s_add_u32 s84, s28, s0
	s_addc_u32 s85, s29, 0
	s_mul_i32 s0, s1, 0x1d00
	s_add_u32 s96, s28, s0
	s_addc_u32 s97, s29, 0
	global_load_dwordx2 v[0:1], v250, s[84:85] offset:0
	global_load_dwordx2 v[2:3], v250, s[84:85] offset:512
	global_load_dwordx2 v[4:5], v250, s[84:85] offset:1024
	s_lshl_b32 s0, s58, 9
	s_add_u32 s0, s42, s0
	s_addc_u32 s1, s43, 0
	global_load_dwordx2 v[12:13], v250, s[0:1]
	ds_read_b128 v[14:17], v31 offset:4096
	ds_read_b128 v[18:21], v31 offset:24576
	ds_read_b128 v[22:25], v31 offset:3072
	ds_read_b128 v[26:29], v31 offset:23552
	s_waitcnt lgkmcnt(4)
	s_waitcnt vmcnt(8)
	v_mov_b32_e32 v242, v222
	v_mov_b32_e32 v243, v223
	v_mov_b32_e32 v244, v224
	v_mov_b32_e32 v245, v225
	v_mov_b32_e32 v246, v226
	v_mov_b32_e32 v247, v227
	v_lshlrev_b32_e32 v134, 16, v222
	v_and_b32_e32 v222, 0xffff0000, v222
	v_lshlrev_b32_e32 v135, 16, v223
	v_and_b32_e32 v223, 0xffff0000, v223
	v_lshlrev_b32_e32 v136, 16, v224
	v_and_b32_e32 v224, 0xffff0000, v224
	v_lshlrev_b32_e32 v137, 16, v225
	v_and_b32_e32 v225, 0xffff0000, v225
	v_lshlrev_b32_e32 v138, 16, v226
	v_and_b32_e32 v226, 0xffff0000, v226
	v_lshlrev_b32_e32 v139, 16, v227
	v_and_b32_e32 v227, 0xffff0000, v227
	v_lshlrev_b32_e32 v140, 16, v228
	v_and_b32_e32 v228, 0xffff0000, v228
	v_lshlrev_b32_e32 v141, 16, v229
	v_and_b32_e32 v229, 0xffff0000, v229
	v_lshlrev_b32_e32 v142, 16, v230
	v_and_b32_e32 v230, 0xffff0000, v230
	v_lshlrev_b32_e32 v143, 16, v231
	v_and_b32_e32 v231, 0xffff0000, v231
	v_lshlrev_b32_e32 v144, 16, v232
	v_and_b32_e32 v232, 0xffff0000, v232
	v_lshlrev_b32_e32 v145, 16, v233
	v_and_b32_e32 v233, 0xffff0000, v233
	v_lshlrev_b32_e32 v146, 16, v234
	v_and_b32_e32 v234, 0xffff0000, v234
	v_lshlrev_b32_e32 v147, 16, v235
	v_and_b32_e32 v235, 0xffff0000, v235
	v_fma_f32 v140, s59, v140, -v134
	v_fma_f32 v228, s59, v228, -v222
	v_fma_f32 v141, s59, v141, -v135
	v_fma_f32 v229, s59, v229, -v223
	v_fmac_f32_e32 v134, v210, v140
	v_fmac_f32_e32 v222, v211, v228
	v_fmac_f32_e32 v135, v212, v141
	v_fmac_f32_e32 v223, v213, v229
	v_fma_f32 v142, s59, v142, -v136
	v_fma_f32 v230, s59, v230, -v224
	v_fma_f32 v143, s59, v143, -v137
	v_fma_f32 v231, s59, v231, -v225
	v_fmac_f32_e32 v136, v214, v142
	v_fmac_f32_e32 v224, v215, v230
	v_fmac_f32_e32 v137, v216, v143
	v_fmac_f32_e32 v225, v217, v231
	v_fma_f32 v144, s59, v144, -v138
	v_fma_f32 v232, s59, v232, -v226
	v_fma_f32 v145, s59, v145, -v139
	v_fma_f32 v233, s59, v233, -v227
	v_fmac_f32_e32 v138, v218, v144
	v_fmac_f32_e32 v226, v219, v232
	v_fmac_f32_e32 v139, v220, v145
	v_fmac_f32_e32 v227, v221, v233
	v_mul_f32_e32 v148, v198, v136
	v_mul_f32_e32 v149, v199, v224
	v_mul_f32_e32 v150, v200, v137
	v_mul_f32_e32 v151, v201, v225
	v_mul_f32_e32 v176, v148, v148
	v_fmac_f32_e32 v176, v149, v149
	v_fmac_f32_e32 v176, v150, v150
	v_fmac_f32_e32 v176, v151, v151
	s_waitcnt lgkmcnt(2)
	v_add_f32_e32 v18, v194, v18
	v_add_f32_e32 v19, v195, v19
	v_add_f32_e32 v20, v196, v20
	v_add_f32_e32 v21, v197, v21
	v_add_f32_dpp v176, v176, v176 quad_perm:[1,0,3,2] row_mask:0xf bank_mask:0xf bound_ctrl:1
	v_mul_f32_e32 v18, 0xbfb8aa3b, v18
	v_mul_f32_e32 v19, 0xbfb8aa3b, v19
	v_mul_f32_e32 v20, 0xbfb8aa3b, v20
	v_mul_f32_e32 v21, 0xbfb8aa3b, v21
	v_add_f32_dpp v176, v176, v176 quad_perm:[2,3,0,1] row_mask:0xf bank_mask:0xf bound_ctrl:1
	v_exp_f32_e32 v18, v18
	v_exp_f32_e32 v19, v19
	v_exp_f32_e32 v20, v20
	v_exp_f32_e32 v21, v21
	v_add_f32_dpp v176, v176, v176 row_half_mirror row_mask:0xf bank_mask:0xf bound_ctrl:1
	v_add_f32_e32 v18, 1.0, v18
	v_add_f32_e32 v19, 1.0, v19
	v_add_f32_e32 v20, 1.0, v20
	v_add_f32_e32 v21, 1.0, v21
	v_add_f32_dpp v176, v176, v176 row_mirror row_mask:0xf bank_mask:0xf bound_ctrl:1
	v_rcp_f32_e32 v18, v18
	v_rcp_f32_e32 v19, v19
	v_rcp_f32_e32 v20, v20
	v_rcp_f32_e32 v21, v21
	v_sqrt_f32_e32 v176, v176
	v_add_f32_e32 v14, v190, v14
	v_add_f32_e32 v15, v191, v15
	v_add_f32_e32 v16, v192, v16
	v_add_f32_e32 v17, v193, v17
	v_max_f32_e32 v176, 0x2b8cbccc, v176
	v_mul_f32_e32 v14, 0xbfb8aa3b, v14
	v_mul_f32_e32 v15, 0xbfb8aa3b, v15
	v_mul_f32_e32 v16, 0xbfb8aa3b, v16
	v_mul_f32_e32 v17, 0xbfb8aa3b, v17
	v_rcp_f32_e32 v178, v176
	v_exp_f32_e32 v14, v14
	v_exp_f32_e32 v15, v15
	v_exp_f32_e32 v16, v16
	v_exp_f32_e32 v17, v17
	v_add_f32_e32 v14, 1.0, v14
	v_add_f32_e32 v15, 1.0, v15
	v_add_f32_e32 v16, 1.0, v16
	v_add_f32_e32 v17, 1.0, v17
	v_rcp_f32_e32 v14, v14
	v_rcp_f32_e32 v15, v15
	v_rcp_f32_e32 v16, v16
	v_rcp_f32_e32 v17, v17
	v_mul_f32_e32 v14, 0xbf1b4598, v14
	v_mul_f32_e32 v15, 0xbf1b4598, v15
	v_mul_f32_e32 v16, 0xbf1b4598, v16
	v_mul_f32_e32 v17, 0xbf1b4598, v17
	v_mul_f32_e32 v14, 0x3fb8aa3b, v14
	v_mul_f32_e32 v15, 0x3fb8aa3b, v15
	v_mul_f32_e32 v16, 0x3fb8aa3b, v16
	v_mul_f32_e32 v17, 0x3fb8aa3b, v17
	v_exp_f32_e32 v14, v14
	v_exp_f32_e32 v15, v15
	v_exp_f32_e32 v16, v16
	v_exp_f32_e32 v17, v17
	v_add_f32_e32 v152, -1.0, v18
	v_add_f32_e32 v153, -1.0, v19
	v_add_f32_e32 v154, -1.0, v20
	v_add_f32_e32 v155, -1.0, v21
	v_fma_f32 v152, v202, v152, 1.0
	v_fma_f32 v153, v203, v153, 1.0
	v_fma_f32 v154, v204, v154, 1.0
	v_fma_f32 v155, v205, v155, 1.0
	v_mul_f32_e32 v152, v136, v152
	v_mul_f32_e32 v153, v224, v153
	v_mul_f32_e32 v154, v137, v154
	v_mul_f32_e32 v155, v225, v155
	v_mul_f32_e32 v156, v134, v152
	v_mul_f32_e32 v157, v222, v153
	v_mul_f32_e32 v158, v135, v154
	v_mul_f32_e32 v159, v223, v155
	v_mul_f32_e32 v177, v206, v156
	v_fmac_f32_e32 v177, v207, v157
	v_fmac_f32_e32 v177, v208, v158
	v_fmac_f32_e32 v177, v209, v159
	v_mul_f32_e32 v148, v148, v178
	v_mul_f32_e32 v149, v149, v178
	v_add_f32_dpp v177, v177, v177 quad_perm:[1,0,3,2] row_mask:0xf bank_mask:0xf bound_ctrl:1
	v_mul_f32_e32 v150, v150, v178
	v_mul_f32_e32 v151, v151, v178
	v_add_f32_dpp v177, v177, v177 quad_perm:[2,3,0,1] row_mask:0xf bank_mask:0xf bound_ctrl:1
	v_mul_f32_e32 v18, v18, v148
	v_mul_f32_e32 v19, v19, v149
	v_add_f32_dpp v177, v177, v177 row_half_mirror row_mask:0xf bank_mask:0xf bound_ctrl:1
	v_mul_f32_e32 v20, v20, v150
	v_mul_f32_e32 v21, v21, v151
	v_add_f32_dpp v177, v177, v177 row_mirror row_mask:0xf bank_mask:0xf bound_ctrl:1
	s_lshl_b32 s0, s56, 9
	s_add_u32 s62, s34, s0
	s_addc_u32 s63, s35, 0
	v_fmac_f32_e32 v146, v138, v177
	v_fmac_f32_e32 v234, v226, v177
	v_fmac_f32_e32 v147, v139, v177
	v_fmac_f32_e32 v235, v227, v177
	v_cvt_pk_bf16_f32 v72, v134, v222
	v_cvt_pk_bf16_f32 v73, v135, v223
	global_store_dwordx2 v250, v[72:73], s[62:63]
	v_cvt_pk_bf16_f32 v74, v14, v15
	v_cvt_pk_bf16_f32 v75, v16, v17
	s_add_u32 s0, s62, 0x500000
	s_addc_u32 s1, s63, 0
	global_store_dwordx2 v250, v[74:75], s[0:1]
	v_cvt_pk_bf16_f32 v180, v152, v153
	v_cvt_pk_bf16_f32 v181, v154, v155
	s_add_u32 s0, s62, 0xa00000
	s_addc_u32 s1, s63, 0
	global_store_dwordx2 v250, v[180:181], s[0:1]
	v_cvt_pk_bf16_f32 v72, v138, v226
	v_cvt_pk_bf16_f32 v73, v139, v227
	s_add_u32 s0, s62, 0xf00000
	s_addc_u32 s1, s63, 0
	global_store_dwordx2 v250, v[72:73], s[0:1]
	v_cvt_pk_bf16_f32 v74, v148, v149
	v_cvt_pk_bf16_f32 v75, v150, v151
	s_add_u32 s0, s62, 0x1400000
	s_addc_u32 s1, s63, 0
	global_store_dwordx2 v250, v[74:75], s[0:1]
	v_cvt_pk_bf16_f32 v180, v18, v19
	v_cvt_pk_bf16_f32 v181, v20, v21
	s_add_u32 s0, s62, 0x1900000
	s_addc_u32 s1, s63, 0
	global_store_dwordx2 v250, v[180:181], s[0:1]
	v_cvt_pk_bf16_f32 v72, v146, v234
	v_cvt_pk_bf16_f32 v73, v147, v235
	s_lshl_b32 s0, s56, 9
	s_add_u32 s0, s42, s0
	s_addc_u32 s1, s43, 0
	global_store_dwordx2 v250, v[72:73], s[0:1]
	s_add_i32 s56, s53, 1
	s_cmpk_lt_i32 s56, 0x2000
	s_movk_i32 s0, 0x3ff
	s_cselect_b32 s0, 0xff, s0
	s_and_b32 s1, s56, s0
	s_cmp_lg_u32 s1, s0
	s_cselect_b32 s59, 1.0, 0
	s_cselect_b32 s1, 1, 0
	s_add_i32 s1, s56, s1
	s_mul_i32 s0, s56, 0x1d00
	s_add_u32 s76, s28, s0
	s_addc_u32 s77, s29, 0
	s_mul_i32 s0, s1, 0x1d00
	s_add_u32 s78, s28, s0
	s_addc_u32 s79, s29, 0
	global_load_dwordx2 v[222:223], v250, s[76:77] offset:0
	global_load_dwordx2 v[224:225], v250, s[76:77] offset:512
	global_load_dwordx2 v[226:227], v250, s[76:77] offset:1024
	s_lshl_b32 s0, s56, 9
	s_add_u32 s0, s42, s0
	s_addc_u32 s1, s43, 0
	global_load_dwordx2 v[234:235], v250, s[0:1]
	ds_read_b128 v[14:17], v31 offset:2048
	ds_read_b128 v[18:21], v31 offset:22528
	s_waitcnt vmcnt(15)
	v_mov_b32_e32 v228, v236
	v_mov_b32_e32 v229, v237
	v_mov_b32_e32 v230, v238
	v_mov_b32_e32 v231, v239
	v_mov_b32_e32 v232, v240
	v_mov_b32_e32 v233, v241
	v_lshlrev_b32_e32 v134, 16, v236
	v_and_b32_e32 v236, 0xffff0000, v236
	v_lshlrev_b32_e32 v135, 16, v237
	v_and_b32_e32 v237, 0xffff0000, v237
	v_lshlrev_b32_e32 v136, 16, v238
	v_and_b32_e32 v238, 0xffff0000, v238
	v_lshlrev_b32_e32 v137, 16, v239
	v_and_b32_e32 v239, 0xffff0000, v239
	v_lshlrev_b32_e32 v138, 16, v240
	v_and_b32_e32 v240, 0xffff0000, v240
	v_lshlrev_b32_e32 v139, 16, v241
	v_and_b32_e32 v241, 0xffff0000, v241
	v_lshlrev_b32_e32 v140, 16, v242
	v_and_b32_e32 v242, 0xffff0000, v242
	v_lshlrev_b32_e32 v141, 16, v243
	v_and_b32_e32 v243, 0xffff0000, v243
	v_lshlrev_b32_e32 v142, 16, v244
	v_and_b32_e32 v244, 0xffff0000, v244
	v_lshlrev_b32_e32 v143, 16, v245
	v_and_b32_e32 v245, 0xffff0000, v245
	v_lshlrev_b32_e32 v144, 16, v246
	v_and_b32_e32 v246, 0xffff0000, v246
	v_lshlrev_b32_e32 v145, 16, v247
	v_and_b32_e32 v247, 0xffff0000, v247
	v_lshlrev_b32_e32 v146, 16, v248
	v_and_b32_e32 v248, 0xffff0000, v248
	v_lshlrev_b32_e32 v147, 16, v249
	v_and_b32_e32 v249, 0xffff0000, v249
	v_fma_f32 v140, s60, v140, -v134
	v_fma_f32 v242, s60, v242, -v236
	v_fma_f32 v141, s60, v141, -v135
	v_fma_f32 v243, s60, v243, -v237
	v_fmac_f32_e32 v134, v210, v140
	v_fmac_f32_e32 v236, v211, v242
	v_fmac_f32_e32 v135, v212, v141
	v_fmac_f32_e32 v237, v213, v243
	v_fma_f32 v142, s60, v142, -v136
	v_fma_f32 v244, s60, v244, -v238
	v_fma_f32 v143, s60, v143, -v137
	v_fma_f32 v245, s60, v245, -v239
	v_fmac_f32_e32 v136, v214, v142
	v_fmac_f32_e32 v238, v215, v244
	v_fmac_f32_e32 v137, v216, v143
	v_fmac_f32_e32 v239, v217, v245
	v_fma_f32 v144, s60, v144, -v138
	v_fma_f32 v246, s60, v246, -v240
	v_fma_f32 v145, s60, v145, -v139
	v_fma_f32 v247, s60, v247, -v241
	v_fmac_f32_e32 v138, v218, v144
	v_fmac_f32_e32 v240, v219, v246
	v_fmac_f32_e32 v139, v220, v145
	v_fmac_f32_e32 v241, v221, v247
	v_mul_f32_e32 v148, v198, v136
	v_mul_f32_e32 v149, v199, v238
	v_mul_f32_e32 v150, v200, v137
	v_mul_f32_e32 v151, v201, v239
	v_mul_f32_e32 v176, v148, v148
	v_fmac_f32_e32 v176, v149, v149
	v_fmac_f32_e32 v176, v150, v150
	v_fmac_f32_e32 v176, v151, v151
	s_waitcnt lgkmcnt(2)
	v_add_f32_e32 v26, v194, v26
	v_add_f32_e32 v27, v195, v27
	v_add_f32_e32 v28, v196, v28
	v_add_f32_e32 v29, v197, v29
	v_add_f32_dpp v176, v176, v176 quad_perm:[1,0,3,2] row_mask:0xf bank_mask:0xf bound_ctrl:1
	v_mul_f32_e32 v26, 0xbfb8aa3b, v26
	v_mul_f32_e32 v27, 0xbfb8aa3b, v27
	v_mul_f32_e32 v28, 0xbfb8aa3b, v28
	v_mul_f32_e32 v29, 0xbfb8aa3b, v29
	v_add_f32_dpp v176, v176, v176 quad_perm:[2,3,0,1] row_mask:0xf bank_mask:0xf bound_ctrl:1
	v_exp_f32_e32 v26, v26
	v_exp_f32_e32 v27, v27
	v_exp_f32_e32 v28, v28
	v_exp_f32_e32 v29, v29
	v_add_f32_dpp v176, v176, v176 row_half_mirror row_mask:0xf bank_mask:0xf bound_ctrl:1
	v_add_f32_e32 v26, 1.0, v26
	v_add_f32_e32 v27, 1.0, v27
	v_add_f32_e32 v28, 1.0, v28
	v_add_f32_e32 v29, 1.0, v29
	v_add_f32_dpp v176, v176, v176 row_mirror row_mask:0xf bank_mask:0xf bound_ctrl:1
	v_rcp_f32_e32 v26, v26
	v_rcp_f32_e32 v27, v27
	v_rcp_f32_e32 v28, v28
	v_rcp_f32_e32 v29, v29
	v_sqrt_f32_e32 v176, v176
	v_add_f32_e32 v22, v190, v22
	v_add_f32_e32 v23, v191, v23
	v_add_f32_e32 v24, v192, v24
	v_add_f32_e32 v25, v193, v25
	v_max_f32_e32 v176, 0x2b8cbccc, v176
	v_mul_f32_e32 v22, 0xbfb8aa3b, v22
	v_mul_f32_e32 v23, 0xbfb8aa3b, v23
	v_mul_f32_e32 v24, 0xbfb8aa3b, v24
	v_mul_f32_e32 v25, 0xbfb8aa3b, v25
	v_rcp_f32_e32 v178, v176
	v_exp_f32_e32 v22, v22
	v_exp_f32_e32 v23, v23
	v_exp_f32_e32 v24, v24
	v_exp_f32_e32 v25, v25
	v_add_f32_e32 v22, 1.0, v22
	v_add_f32_e32 v23, 1.0, v23
	v_add_f32_e32 v24, 1.0, v24
	v_add_f32_e32 v25, 1.0, v25
	v_rcp_f32_e32 v22, v22
	v_rcp_f32_e32 v23, v23
	v_rcp_f32_e32 v24, v24
	v_rcp_f32_e32 v25, v25
	v_mul_f32_e32 v22, 0xbf1b4598, v22
	v_mul_f32_e32 v23, 0xbf1b4598, v23
	v_mul_f32_e32 v24, 0xbf1b4598, v24
	v_mul_f32_e32 v25, 0xbf1b4598, v25
	v_mul_f32_e32 v22, 0x3fb8aa3b, v22
	v_mul_f32_e32 v23, 0x3fb8aa3b, v23
	v_mul_f32_e32 v24, 0x3fb8aa3b, v24
	v_mul_f32_e32 v25, 0x3fb8aa3b, v25
	v_exp_f32_e32 v22, v22
	v_exp_f32_e32 v23, v23
	v_exp_f32_e32 v24, v24
	v_exp_f32_e32 v25, v25
	v_add_f32_e32 v152, -1.0, v26
	v_add_f32_e32 v153, -1.0, v27
	v_add_f32_e32 v154, -1.0, v28
	v_add_f32_e32 v155, -1.0, v29
	v_fma_f32 v152, v202, v152, 1.0
	v_fma_f32 v153, v203, v153, 1.0
	v_fma_f32 v154, v204, v154, 1.0
	v_fma_f32 v155, v205, v155, 1.0
	v_mul_f32_e32 v152, v136, v152
	v_mul_f32_e32 v153, v238, v153
	v_mul_f32_e32 v154, v137, v154
	v_mul_f32_e32 v155, v239, v155
	v_mul_f32_e32 v156, v134, v152
	v_mul_f32_e32 v157, v236, v153
	v_mul_f32_e32 v158, v135, v154
	v_mul_f32_e32 v159, v237, v155
	v_mul_f32_e32 v177, v206, v156
	v_fmac_f32_e32 v177, v207, v157
	v_fmac_f32_e32 v177, v208, v158
	v_fmac_f32_e32 v177, v209, v159
	v_mul_f32_e32 v148, v148, v178
	v_mul_f32_e32 v149, v149, v178
	v_add_f32_dpp v177, v177, v177 quad_perm:[1,0,3,2] row_mask:0xf bank_mask:0xf bound_ctrl:1
	v_mul_f32_e32 v150, v150, v178
	v_mul_f32_e32 v151, v151, v178
	v_add_f32_dpp v177, v177, v177 quad_perm:[2,3,0,1] row_mask:0xf bank_mask:0xf bound_ctrl:1
	v_mul_f32_e32 v26, v26, v148
	v_mul_f32_e32 v27, v27, v149
	v_add_f32_dpp v177, v177, v177 row_half_mirror row_mask:0xf bank_mask:0xf bound_ctrl:1
	v_mul_f32_e32 v28, v28, v150
	v_mul_f32_e32 v29, v29, v151
	v_add_f32_dpp v177, v177, v177 row_mirror row_mask:0xf bank_mask:0xf bound_ctrl:1
	s_lshl_b32 s0, s57, 9
	s_add_u32 s62, s34, s0
	s_addc_u32 s63, s35, 0
	v_fmac_f32_e32 v146, v138, v177
	v_fmac_f32_e32 v248, v240, v177
	v_fmac_f32_e32 v147, v139, v177
	v_fmac_f32_e32 v249, v241, v177
	v_cvt_pk_bf16_f32 v72, v134, v236
	v_cvt_pk_bf16_f32 v73, v135, v237
	global_store_dwordx2 v250, v[72:73], s[62:63]
	v_cvt_pk_bf16_f32 v74, v22, v23
	v_cvt_pk_bf16_f32 v75, v24, v25
	s_add_u32 s0, s62, 0x500000
	s_addc_u32 s1, s63, 0
	global_store_dwordx2 v250, v[74:75], s[0:1]
	v_cvt_pk_bf16_f32 v180, v152, v153
	v_cvt_pk_bf16_f32 v181, v154, v155
	s_add_u32 s0, s62, 0xa00000
	s_addc_u32 s1, s63, 0
	global_store_dwordx2 v250, v[180:181], s[0:1]
	v_cvt_pk_bf16_f32 v72, v138, v240
	v_cvt_pk_bf16_f32 v73, v139, v241
	s_add_u32 s0, s62, 0xf00000
	s_addc_u32 s1, s63, 0
	global_store_dwordx2 v250, v[72:73], s[0:1]
	v_cvt_pk_bf16_f32 v74, v148, v149
	v_cvt_pk_bf16_f32 v75, v150, v151
	s_add_u32 s0, s62, 0x1400000
	s_addc_u32 s1, s63, 0
	global_store_dwordx2 v250, v[74:75], s[0:1]
	v_cvt_pk_bf16_f32 v180, v26, v27
	v_cvt_pk_bf16_f32 v181, v28, v29
	s_add_u32 s0, s62, 0x1900000
	s_addc_u32 s1, s63, 0
	global_store_dwordx2 v250, v[180:181], s[0:1]
	v_cvt_pk_bf16_f32 v72, v146, v248
	v_cvt_pk_bf16_f32 v73, v147, v249
	s_lshl_b32 s0, s57, 9
	s_add_u32 s0, s42, s0
	s_addc_u32 s1, s43, 0
	global_store_dwordx2 v250, v[72:73], s[0:1]
	s_add_i32 s57, s53, 0
	s_cmpk_lt_i32 s57, 0x2000
	s_movk_i32 s0, 0x3ff
	s_cselect_b32 s0, 0xff, s0
	s_and_b32 s1, s57, s0
	s_cmp_lg_u32 s1, s0
	s_cselect_b32 s60, 1.0, 0
	s_cselect_b32 s1, 1, 0
	s_add_i32 s1, s57, s1
	s_mul_i32 s0, s57, 0x1d00
	s_add_u32 s80, s28, s0
	s_addc_u32 s81, s29, 0
	s_mul_i32 s0, s1, 0x1d00
	s_add_u32 s82, s28, s0
	s_addc_u32 s83, s29, 0
	global_load_dwordx2 v[236:237], v250, s[80:81] offset:0
	global_load_dwordx2 v[238:239], v250, s[80:81] offset:512
	global_load_dwordx2 v[240:241], v250, s[80:81] offset:1024
	s_lshl_b32 s0, s57, 9
	s_add_u32 s0, s42, s0
	s_addc_u32 s1, s43, 0
	global_load_dwordx2 v[248:249], v250, s[0:1]
	ds_read_b128 v[22:25], v31 offset:1024
	ds_read_b128 v[26:29], v31 offset:21504
	s_waitcnt vmcnt(22)
	v_mov_b32_e32 v242, v0
	v_mov_b32_e32 v243, v1
	v_mov_b32_e32 v244, v2
	v_mov_b32_e32 v245, v3
	v_mov_b32_e32 v246, v4
	v_mov_b32_e32 v247, v5
	v_lshlrev_b32_e32 v134, 16, v0
	v_and_b32_e32 v0, 0xffff0000, v0
	v_lshlrev_b32_e32 v135, 16, v1
	v_and_b32_e32 v1, 0xffff0000, v1
	v_lshlrev_b32_e32 v136, 16, v2
	v_and_b32_e32 v2, 0xffff0000, v2
	v_lshlrev_b32_e32 v137, 16, v3
	v_and_b32_e32 v3, 0xffff0000, v3
	v_lshlrev_b32_e32 v138, 16, v4
	v_and_b32_e32 v4, 0xffff0000, v4
	v_lshlrev_b32_e32 v139, 16, v5
	v_and_b32_e32 v5, 0xffff0000, v5
	v_lshlrev_b32_e32 v140, 16, v228
	v_and_b32_e32 v228, 0xffff0000, v228
	v_lshlrev_b32_e32 v141, 16, v229
	v_and_b32_e32 v229, 0xffff0000, v229
	v_lshlrev_b32_e32 v142, 16, v230
	v_and_b32_e32 v230, 0xffff0000, v230
	v_lshlrev_b32_e32 v143, 16, v231
	v_and_b32_e32 v231, 0xffff0000, v231
	v_lshlrev_b32_e32 v144, 16, v232
	v_and_b32_e32 v232, 0xffff0000, v232
	v_lshlrev_b32_e32 v145, 16, v233
	v_and_b32_e32 v233, 0xffff0000, v233
	v_lshlrev_b32_e32 v146, 16, v12
	v_and_b32_e32 v12, 0xffff0000, v12
	v_lshlrev_b32_e32 v147, 16, v13
	v_and_b32_e32 v13, 0xffff0000, v13
	v_fma_f32 v140, s61, v140, -v134
	v_fma_f32 v228, s61, v228, -v0
	v_fma_f32 v141, s61, v141, -v135
	v_fma_f32 v229, s61, v229, -v1
	v_fmac_f32_e32 v134, v210, v140
	v_fmac_f32_e32 v0, v211, v228
	v_fmac_f32_e32 v135, v212, v141
	v_fmac_f32_e32 v1, v213, v229
	v_fma_f32 v142, s61, v142, -v136
	v_fma_f32 v230, s61, v230, -v2
	v_fma_f32 v143, s61, v143, -v137
	v_fma_f32 v231, s61, v231, -v3
	v_fmac_f32_e32 v136, v214, v142
	v_fmac_f32_e32 v2, v215, v230
	v_fmac_f32_e32 v137, v216, v143
	v_fmac_f32_e32 v3, v217, v231
	v_fma_f32 v144, s61, v144, -v138
	v_fma_f32 v232, s61, v232, -v4
	v_fma_f32 v145, s61, v145, -v139
	v_fma_f32 v233, s61, v233, -v5
	v_fmac_f32_e32 v138, v218, v144
	v_fmac_f32_e32 v4, v219, v232
	v_fmac_f32_e32 v139, v220, v145
	v_fmac_f32_e32 v5, v221, v233
	v_mul_f32_e32 v148, v198, v136
	v_mul_f32_e32 v149, v199, v2
	v_mul_f32_e32 v150, v200, v137
	v_mul_f32_e32 v151, v201, v3
	v_mul_f32_e32 v176, v148, v148
	v_fmac_f32_e32 v176, v149, v149
	v_fmac_f32_e32 v176, v150, v150
	v_fmac_f32_e32 v176, v151, v151
	s_waitcnt lgkmcnt(2)
	v_add_f32_e32 v18, v194, v18
	v_add_f32_e32 v19, v195, v19
	v_add_f32_e32 v20, v196, v20
	v_add_f32_e32 v21, v197, v21
	v_add_f32_dpp v176, v176, v176 quad_perm:[1,0,3,2] row_mask:0xf bank_mask:0xf bound_ctrl:1
	v_mul_f32_e32 v18, 0xbfb8aa3b, v18
	v_mul_f32_e32 v19, 0xbfb8aa3b, v19
	v_mul_f32_e32 v20, 0xbfb8aa3b, v20
	v_mul_f32_e32 v21, 0xbfb8aa3b, v21
	v_add_f32_dpp v176, v176, v176 quad_perm:[2,3,0,1] row_mask:0xf bank_mask:0xf bound_ctrl:1
	v_exp_f32_e32 v18, v18
	v_exp_f32_e32 v19, v19
	v_exp_f32_e32 v20, v20
	v_exp_f32_e32 v21, v21
	v_add_f32_dpp v176, v176, v176 row_half_mirror row_mask:0xf bank_mask:0xf bound_ctrl:1
	v_add_f32_e32 v18, 1.0, v18
	v_add_f32_e32 v19, 1.0, v19
	v_add_f32_e32 v20, 1.0, v20
	v_add_f32_e32 v21, 1.0, v21
	v_add_f32_dpp v176, v176, v176 row_mirror row_mask:0xf bank_mask:0xf bound_ctrl:1
	v_rcp_f32_e32 v18, v18
	v_rcp_f32_e32 v19, v19
	v_rcp_f32_e32 v20, v20
	v_rcp_f32_e32 v21, v21
	v_sqrt_f32_e32 v176, v176
	v_add_f32_e32 v14, v190, v14
	v_add_f32_e32 v15, v191, v15
	v_add_f32_e32 v16, v192, v16
	v_add_f32_e32 v17, v193, v17
	v_max_f32_e32 v176, 0x2b8cbccc, v176
	v_mul_f32_e32 v14, 0xbfb8aa3b, v14
	v_mul_f32_e32 v15, 0xbfb8aa3b, v15
	v_mul_f32_e32 v16, 0xbfb8aa3b, v16
	v_mul_f32_e32 v17, 0xbfb8aa3b, v17
	v_rcp_f32_e32 v178, v176
	v_exp_f32_e32 v14, v14
	v_exp_f32_e32 v15, v15
	v_exp_f32_e32 v16, v16
	v_exp_f32_e32 v17, v17
	v_add_f32_e32 v14, 1.0, v14
	v_add_f32_e32 v15, 1.0, v15
	v_add_f32_e32 v16, 1.0, v16
	v_add_f32_e32 v17, 1.0, v17
	v_rcp_f32_e32 v14, v14
	v_rcp_f32_e32 v15, v15
	v_rcp_f32_e32 v16, v16
	v_rcp_f32_e32 v17, v17
	v_mul_f32_e32 v14, 0xbf1b4598, v14
	v_mul_f32_e32 v15, 0xbf1b4598, v15
	v_mul_f32_e32 v16, 0xbf1b4598, v16
	v_mul_f32_e32 v17, 0xbf1b4598, v17
	v_mul_f32_e32 v14, 0x3fb8aa3b, v14
	v_mul_f32_e32 v15, 0x3fb8aa3b, v15
	v_mul_f32_e32 v16, 0x3fb8aa3b, v16
	v_mul_f32_e32 v17, 0x3fb8aa3b, v17
	v_exp_f32_e32 v14, v14
	v_exp_f32_e32 v15, v15
	v_exp_f32_e32 v16, v16
	v_exp_f32_e32 v17, v17
	v_add_f32_e32 v152, -1.0, v18
	v_add_f32_e32 v153, -1.0, v19
	v_add_f32_e32 v154, -1.0, v20
	v_add_f32_e32 v155, -1.0, v21
	v_fma_f32 v152, v202, v152, 1.0
	v_fma_f32 v153, v203, v153, 1.0
	v_fma_f32 v154, v204, v154, 1.0
	v_fma_f32 v155, v205, v155, 1.0
	v_mul_f32_e32 v152, v136, v152
	v_mul_f32_e32 v153, v2, v153
	v_mul_f32_e32 v154, v137, v154
	v_mul_f32_e32 v155, v3, v155
	v_mul_f32_e32 v156, v134, v152
	v_mul_f32_e32 v157, v0, v153
	v_mul_f32_e32 v158, v135, v154
	v_mul_f32_e32 v159, v1, v155
	v_mul_f32_e32 v177, v206, v156
	v_fmac_f32_e32 v177, v207, v157
	v_fmac_f32_e32 v177, v208, v158
	v_fmac_f32_e32 v177, v209, v159
	v_mul_f32_e32 v148, v148, v178
	v_mul_f32_e32 v149, v149, v178
	v_add_f32_dpp v177, v177, v177 quad_perm:[1,0,3,2] row_mask:0xf bank_mask:0xf bound_ctrl:1
	v_mul_f32_e32 v150, v150, v178
	v_mul_f32_e32 v151, v151, v178
	v_add_f32_dpp v177, v177, v177 quad_perm:[2,3,0,1] row_mask:0xf bank_mask:0xf bound_ctrl:1
	v_mul_f32_e32 v18, v18, v148
	v_mul_f32_e32 v19, v19, v149
	v_add_f32_dpp v177, v177, v177 row_half_mirror row_mask:0xf bank_mask:0xf bound_ctrl:1
	v_mul_f32_e32 v20, v20, v150
	v_mul_f32_e32 v21, v21, v151
	v_add_f32_dpp v177, v177, v177 row_mirror row_mask:0xf bank_mask:0xf bound_ctrl:1
	s_lshl_b32 s0, s58, 9
	s_add_u32 s62, s34, s0
	s_addc_u32 s63, s35, 0
	v_fmac_f32_e32 v146, v138, v177
	v_fmac_f32_e32 v12, v4, v177
	v_fmac_f32_e32 v147, v139, v177
	v_fmac_f32_e32 v13, v5, v177
	v_cvt_pk_bf16_f32 v72, v134, v0
	v_cvt_pk_bf16_f32 v73, v135, v1
	global_store_dwordx2 v250, v[72:73], s[62:63]
	v_cvt_pk_bf16_f32 v74, v14, v15
	v_cvt_pk_bf16_f32 v75, v16, v17
	s_add_u32 s0, s62, 0x500000
	s_addc_u32 s1, s63, 0
	global_store_dwordx2 v250, v[74:75], s[0:1]
	v_cvt_pk_bf16_f32 v180, v152, v153
	v_cvt_pk_bf16_f32 v181, v154, v155
	s_add_u32 s0, s62, 0xa00000
	s_addc_u32 s1, s63, 0
	global_store_dwordx2 v250, v[180:181], s[0:1]
	v_cvt_pk_bf16_f32 v72, v138, v4
	v_cvt_pk_bf16_f32 v73, v139, v5
	s_add_u32 s0, s62, 0xf00000
	s_addc_u32 s1, s63, 0
	global_store_dwordx2 v250, v[72:73], s[0:1]
	v_cvt_pk_bf16_f32 v74, v148, v149
	v_cvt_pk_bf16_f32 v75, v150, v151
	s_add_u32 s0, s62, 0x1400000
	s_addc_u32 s1, s63, 0
	global_store_dwordx2 v250, v[74:75], s[0:1]
	v_cvt_pk_bf16_f32 v180, v18, v19
	v_cvt_pk_bf16_f32 v181, v20, v21
	s_add_u32 s0, s62, 0x1900000
	s_addc_u32 s1, s63, 0
	global_store_dwordx2 v250, v[180:181], s[0:1]
	v_cvt_pk_bf16_f32 v72, v146, v12
	v_cvt_pk_bf16_f32 v73, v147, v13
	s_lshl_b32 s0, s58, 9
	s_add_u32 s0, s42, s0
	s_addc_u32 s1, s43, 0
	global_store_dwordx2 v250, v[72:73], s[0:1]
	ds_read_b128 v[14:17], v31 offset:0
	ds_read_b128 v[18:21], v31 offset:20480
	s_waitcnt vmcnt(18)
	v_mov_b32_e32 v228, v222
	v_mov_b32_e32 v229, v223
	v_mov_b32_e32 v230, v224
	v_mov_b32_e32 v231, v225
	v_mov_b32_e32 v232, v226
	v_mov_b32_e32 v233, v227
	v_lshlrev_b32_e32 v134, 16, v222
	v_and_b32_e32 v222, 0xffff0000, v222
	v_lshlrev_b32_e32 v135, 16, v223
	v_and_b32_e32 v223, 0xffff0000, v223
	v_lshlrev_b32_e32 v136, 16, v224
	v_and_b32_e32 v224, 0xffff0000, v224
	v_lshlrev_b32_e32 v137, 16, v225
	v_and_b32_e32 v225, 0xffff0000, v225
	v_lshlrev_b32_e32 v138, 16, v226
	v_and_b32_e32 v226, 0xffff0000, v226
	v_lshlrev_b32_e32 v139, 16, v227
	v_and_b32_e32 v227, 0xffff0000, v227
	v_lshlrev_b32_e32 v140, 16, v242
	v_and_b32_e32 v242, 0xffff0000, v242
	v_lshlrev_b32_e32 v141, 16, v243
	v_and_b32_e32 v243, 0xffff0000, v243
	v_lshlrev_b32_e32 v142, 16, v244
	v_and_b32_e32 v244, 0xffff0000, v244
	v_lshlrev_b32_e32 v143, 16, v245
	v_and_b32_e32 v245, 0xffff0000, v245
	v_lshlrev_b32_e32 v144, 16, v246
	v_and_b32_e32 v246, 0xffff0000, v246
	v_lshlrev_b32_e32 v145, 16, v247
	v_and_b32_e32 v247, 0xffff0000, v247
	v_lshlrev_b32_e32 v146, 16, v234
	v_and_b32_e32 v234, 0xffff0000, v234
	v_lshlrev_b32_e32 v147, 16, v235
	v_and_b32_e32 v235, 0xffff0000, v235
	v_fma_f32 v140, s59, v140, -v134
	v_fma_f32 v242, s59, v242, -v222
	v_fma_f32 v141, s59, v141, -v135
	v_fma_f32 v243, s59, v243, -v223
	v_fmac_f32_e32 v134, v210, v140
	v_fmac_f32_e32 v222, v211, v242
	v_fmac_f32_e32 v135, v212, v141
	v_fmac_f32_e32 v223, v213, v243
	v_fma_f32 v142, s59, v142, -v136
	v_fma_f32 v244, s59, v244, -v224
	v_fma_f32 v143, s59, v143, -v137
	v_fma_f32 v245, s59, v245, -v225
	v_fmac_f32_e32 v136, v214, v142
	v_fmac_f32_e32 v224, v215, v244
	v_fmac_f32_e32 v137, v216, v143
	v_fmac_f32_e32 v225, v217, v245
	v_fma_f32 v144, s59, v144, -v138
	v_fma_f32 v246, s59, v246, -v226
	v_fma_f32 v145, s59, v145, -v139
	v_fma_f32 v247, s59, v247, -v227
	v_fmac_f32_e32 v138, v218, v144
	v_fmac_f32_e32 v226, v219, v246
	v_fmac_f32_e32 v139, v220, v145
	v_fmac_f32_e32 v227, v221, v247
	v_mul_f32_e32 v148, v198, v136
	v_mul_f32_e32 v149, v199, v224
	v_mul_f32_e32 v150, v200, v137
	v_mul_f32_e32 v151, v201, v225
	v_mul_f32_e32 v176, v148, v148
	v_fmac_f32_e32 v176, v149, v149
	v_fmac_f32_e32 v176, v150, v150
	v_fmac_f32_e32 v176, v151, v151
	s_waitcnt lgkmcnt(2)
	v_add_f32_e32 v26, v194, v26
	v_add_f32_e32 v27, v195, v27
	v_add_f32_e32 v28, v196, v28
	v_add_f32_e32 v29, v197, v29
	v_add_f32_dpp v176, v176, v176 quad_perm:[1,0,3,2] row_mask:0xf bank_mask:0xf bound_ctrl:1
	v_mul_f32_e32 v26, 0xbfb8aa3b, v26
	v_mul_f32_e32 v27, 0xbfb8aa3b, v27
	v_mul_f32_e32 v28, 0xbfb8aa3b, v28
	v_mul_f32_e32 v29, 0xbfb8aa3b, v29
	v_add_f32_dpp v176, v176, v176 quad_perm:[2,3,0,1] row_mask:0xf bank_mask:0xf bound_ctrl:1
	v_exp_f32_e32 v26, v26
	v_exp_f32_e32 v27, v27
	v_exp_f32_e32 v28, v28
	v_exp_f32_e32 v29, v29
	v_add_f32_dpp v176, v176, v176 row_half_mirror row_mask:0xf bank_mask:0xf bound_ctrl:1
	v_add_f32_e32 v26, 1.0, v26
	v_add_f32_e32 v27, 1.0, v27
	v_add_f32_e32 v28, 1.0, v28
	v_add_f32_e32 v29, 1.0, v29
	v_add_f32_dpp v176, v176, v176 row_mirror row_mask:0xf bank_mask:0xf bound_ctrl:1
	v_rcp_f32_e32 v26, v26
	v_rcp_f32_e32 v27, v27
	v_rcp_f32_e32 v28, v28
	v_rcp_f32_e32 v29, v29
	v_sqrt_f32_e32 v176, v176
	v_add_f32_e32 v22, v190, v22
	v_add_f32_e32 v23, v191, v23
	v_add_f32_e32 v24, v192, v24
	v_add_f32_e32 v25, v193, v25
	v_max_f32_e32 v176, 0x2b8cbccc, v176
	v_mul_f32_e32 v22, 0xbfb8aa3b, v22
	v_mul_f32_e32 v23, 0xbfb8aa3b, v23
	v_mul_f32_e32 v24, 0xbfb8aa3b, v24
	v_mul_f32_e32 v25, 0xbfb8aa3b, v25
	v_rcp_f32_e32 v178, v176
	v_exp_f32_e32 v22, v22
	v_exp_f32_e32 v23, v23
	v_exp_f32_e32 v24, v24
	v_exp_f32_e32 v25, v25
	v_add_f32_e32 v22, 1.0, v22
	v_add_f32_e32 v23, 1.0, v23
	v_add_f32_e32 v24, 1.0, v24
	v_add_f32_e32 v25, 1.0, v25
	v_rcp_f32_e32 v22, v22
	v_rcp_f32_e32 v23, v23
	v_rcp_f32_e32 v24, v24
	v_rcp_f32_e32 v25, v25
	v_mul_f32_e32 v22, 0xbf1b4598, v22
	v_mul_f32_e32 v23, 0xbf1b4598, v23
	v_mul_f32_e32 v24, 0xbf1b4598, v24
	v_mul_f32_e32 v25, 0xbf1b4598, v25
	v_mul_f32_e32 v22, 0x3fb8aa3b, v22
	v_mul_f32_e32 v23, 0x3fb8aa3b, v23
	v_mul_f32_e32 v24, 0x3fb8aa3b, v24
	v_mul_f32_e32 v25, 0x3fb8aa3b, v25
	v_exp_f32_e32 v22, v22
	v_exp_f32_e32 v23, v23
	v_exp_f32_e32 v24, v24
	v_exp_f32_e32 v25, v25
	v_add_f32_e32 v152, -1.0, v26
	v_add_f32_e32 v153, -1.0, v27
	v_add_f32_e32 v154, -1.0, v28
	v_add_f32_e32 v155, -1.0, v29
	v_fma_f32 v152, v202, v152, 1.0
	v_fma_f32 v153, v203, v153, 1.0
	v_fma_f32 v154, v204, v154, 1.0
	v_fma_f32 v155, v205, v155, 1.0
	v_mul_f32_e32 v152, v136, v152
	v_mul_f32_e32 v153, v224, v153
	v_mul_f32_e32 v154, v137, v154
	v_mul_f32_e32 v155, v225, v155
	v_mul_f32_e32 v156, v134, v152
	v_mul_f32_e32 v157, v222, v153
	v_mul_f32_e32 v158, v135, v154
	v_mul_f32_e32 v159, v223, v155
	v_mul_f32_e32 v177, v206, v156
	v_fmac_f32_e32 v177, v207, v157
	v_fmac_f32_e32 v177, v208, v158
	v_fmac_f32_e32 v177, v209, v159
	v_mul_f32_e32 v148, v148, v178
	v_mul_f32_e32 v149, v149, v178
	v_add_f32_dpp v177, v177, v177 quad_perm:[1,0,3,2] row_mask:0xf bank_mask:0xf bound_ctrl:1
	v_mul_f32_e32 v150, v150, v178
	v_mul_f32_e32 v151, v151, v178
	v_add_f32_dpp v177, v177, v177 quad_perm:[2,3,0,1] row_mask:0xf bank_mask:0xf bound_ctrl:1
	v_mul_f32_e32 v26, v26, v148
	v_mul_f32_e32 v27, v27, v149
	v_add_f32_dpp v177, v177, v177 row_half_mirror row_mask:0xf bank_mask:0xf bound_ctrl:1
	v_mul_f32_e32 v28, v28, v150
	v_mul_f32_e32 v29, v29, v151
	v_add_f32_dpp v177, v177, v177 row_mirror row_mask:0xf bank_mask:0xf bound_ctrl:1
	s_lshl_b32 s0, s56, 9
	s_add_u32 s62, s34, s0
	s_addc_u32 s63, s35, 0
	v_fmac_f32_e32 v146, v138, v177
	v_fmac_f32_e32 v234, v226, v177
	v_fmac_f32_e32 v147, v139, v177
	v_fmac_f32_e32 v235, v227, v177
	v_cvt_pk_bf16_f32 v72, v134, v222
	v_cvt_pk_bf16_f32 v73, v135, v223
	global_store_dwordx2 v250, v[72:73], s[62:63]
	v_cvt_pk_bf16_f32 v74, v22, v23
	v_cvt_pk_bf16_f32 v75, v24, v25
	s_add_u32 s0, s62, 0x500000
	s_addc_u32 s1, s63, 0
	global_store_dwordx2 v250, v[74:75], s[0:1]
	v_cvt_pk_bf16_f32 v180, v152, v153
	v_cvt_pk_bf16_f32 v181, v154, v155
	s_add_u32 s0, s62, 0xa00000
	s_addc_u32 s1, s63, 0
	global_store_dwordx2 v250, v[180:181], s[0:1]
	v_cvt_pk_bf16_f32 v72, v138, v226
	v_cvt_pk_bf16_f32 v73, v139, v227
	s_add_u32 s0, s62, 0xf00000
	s_addc_u32 s1, s63, 0
	global_store_dwordx2 v250, v[72:73], s[0:1]
	v_cvt_pk_bf16_f32 v74, v148, v149
	v_cvt_pk_bf16_f32 v75, v150, v151
	s_add_u32 s0, s62, 0x1400000
	s_addc_u32 s1, s63, 0
	global_store_dwordx2 v250, v[74:75], s[0:1]
	v_cvt_pk_bf16_f32 v180, v26, v27
	v_cvt_pk_bf16_f32 v181, v28, v29
	s_add_u32 s0, s62, 0x1900000
	s_addc_u32 s1, s63, 0
	global_store_dwordx2 v250, v[180:181], s[0:1]
	v_cvt_pk_bf16_f32 v72, v146, v234
	v_cvt_pk_bf16_f32 v73, v147, v235
	s_lshl_b32 s0, s56, 9
	s_add_u32 s0, s42, s0
	s_addc_u32 s1, s43, 0
	global_store_dwordx2 v250, v[72:73], s[0:1]
	s_waitcnt vmcnt(14)
	v_lshlrev_b32_e32 v134, 16, v236
	v_and_b32_e32 v236, 0xffff0000, v236
	v_lshlrev_b32_e32 v135, 16, v237
	v_and_b32_e32 v237, 0xffff0000, v237
	v_lshlrev_b32_e32 v136, 16, v238
	v_and_b32_e32 v238, 0xffff0000, v238
	v_lshlrev_b32_e32 v137, 16, v239
	v_and_b32_e32 v239, 0xffff0000, v239
	v_lshlrev_b32_e32 v138, 16, v240
	v_and_b32_e32 v240, 0xffff0000, v240
	v_lshlrev_b32_e32 v139, 16, v241
	v_and_b32_e32 v241, 0xffff0000, v241
	v_lshlrev_b32_e32 v140, 16, v228
	v_and_b32_e32 v228, 0xffff0000, v228
	v_lshlrev_b32_e32 v141, 16, v229
	v_and_b32_e32 v229, 0xffff0000, v229
	v_lshlrev_b32_e32 v142, 16, v230
	v_and_b32_e32 v230, 0xffff0000, v230
	v_lshlrev_b32_e32 v143, 16, v231
	v_and_b32_e32 v231, 0xffff0000, v231
	v_lshlrev_b32_e32 v144, 16, v232
	v_and_b32_e32 v232, 0xffff0000, v232
	v_lshlrev_b32_e32 v145, 16, v233
	v_and_b32_e32 v233, 0xffff0000, v233
	v_lshlrev_b32_e32 v146, 16, v248
	v_and_b32_e32 v248, 0xffff0000, v248
	v_lshlrev_b32_e32 v147, 16, v249
	v_and_b32_e32 v249, 0xffff0000, v249
	v_fma_f32 v140, s60, v140, -v134
	v_fma_f32 v228, s60, v228, -v236
	v_fma_f32 v141, s60, v141, -v135
	v_fma_f32 v229, s60, v229, -v237
	v_fmac_f32_e32 v134, v210, v140
	v_fmac_f32_e32 v236, v211, v228
	v_fmac_f32_e32 v135, v212, v141
	v_fmac_f32_e32 v237, v213, v229
	v_fma_f32 v142, s60, v142, -v136
	v_fma_f32 v230, s60, v230, -v238
	v_fma_f32 v143, s60, v143, -v137
	v_fma_f32 v231, s60, v231, -v239
	v_fmac_f32_e32 v136, v214, v142
	v_fmac_f32_e32 v238, v215, v230
	v_fmac_f32_e32 v137, v216, v143
	v_fmac_f32_e32 v239, v217, v231
	v_fma_f32 v144, s60, v144, -v138
	v_fma_f32 v232, s60, v232, -v240
	v_fma_f32 v145, s60, v145, -v139
	v_fma_f32 v233, s60, v233, -v241
	v_fmac_f32_e32 v138, v218, v144
	v_fmac_f32_e32 v240, v219, v232
	v_fmac_f32_e32 v139, v220, v145
	v_fmac_f32_e32 v241, v221, v233
	v_mul_f32_e32 v148, v198, v136
	v_mul_f32_e32 v149, v199, v238
	v_mul_f32_e32 v150, v200, v137
	v_mul_f32_e32 v151, v201, v239
	v_mul_f32_e32 v176, v148, v148
	v_fmac_f32_e32 v176, v149, v149
	v_fmac_f32_e32 v176, v150, v150
	v_fmac_f32_e32 v176, v151, v151
	s_waitcnt lgkmcnt(0)
	v_add_f32_e32 v18, v194, v18
	v_add_f32_e32 v19, v195, v19
	v_add_f32_e32 v20, v196, v20
	v_add_f32_e32 v21, v197, v21
	v_add_f32_dpp v176, v176, v176 quad_perm:[1,0,3,2] row_mask:0xf bank_mask:0xf bound_ctrl:1
	v_mul_f32_e32 v18, 0xbfb8aa3b, v18
	v_mul_f32_e32 v19, 0xbfb8aa3b, v19
	v_mul_f32_e32 v20, 0xbfb8aa3b, v20
	v_mul_f32_e32 v21, 0xbfb8aa3b, v21
	v_add_f32_dpp v176, v176, v176 quad_perm:[2,3,0,1] row_mask:0xf bank_mask:0xf bound_ctrl:1
	v_exp_f32_e32 v18, v18
	v_exp_f32_e32 v19, v19
	v_exp_f32_e32 v20, v20
	v_exp_f32_e32 v21, v21
	v_add_f32_dpp v176, v176, v176 row_half_mirror row_mask:0xf bank_mask:0xf bound_ctrl:1
	v_add_f32_e32 v18, 1.0, v18
	v_add_f32_e32 v19, 1.0, v19
	v_add_f32_e32 v20, 1.0, v20
	v_add_f32_e32 v21, 1.0, v21
	v_add_f32_dpp v176, v176, v176 row_mirror row_mask:0xf bank_mask:0xf bound_ctrl:1
	v_rcp_f32_e32 v18, v18
	v_rcp_f32_e32 v19, v19
	v_rcp_f32_e32 v20, v20
	v_rcp_f32_e32 v21, v21
	v_sqrt_f32_e32 v176, v176
	v_add_f32_e32 v14, v190, v14
	v_add_f32_e32 v15, v191, v15
	v_add_f32_e32 v16, v192, v16
	v_add_f32_e32 v17, v193, v17
	v_max_f32_e32 v176, 0x2b8cbccc, v176
	v_mul_f32_e32 v14, 0xbfb8aa3b, v14
	v_mul_f32_e32 v15, 0xbfb8aa3b, v15
	v_mul_f32_e32 v16, 0xbfb8aa3b, v16
	v_mul_f32_e32 v17, 0xbfb8aa3b, v17
	v_rcp_f32_e32 v178, v176
	v_exp_f32_e32 v14, v14
	v_exp_f32_e32 v15, v15
	v_exp_f32_e32 v16, v16
	v_exp_f32_e32 v17, v17
	v_add_f32_e32 v14, 1.0, v14
	v_add_f32_e32 v15, 1.0, v15
	v_add_f32_e32 v16, 1.0, v16
	v_add_f32_e32 v17, 1.0, v17
	v_rcp_f32_e32 v14, v14
	v_rcp_f32_e32 v15, v15
	v_rcp_f32_e32 v16, v16
	v_rcp_f32_e32 v17, v17
	v_mul_f32_e32 v14, 0xbf1b4598, v14
	v_mul_f32_e32 v15, 0xbf1b4598, v15
	v_mul_f32_e32 v16, 0xbf1b4598, v16
	v_mul_f32_e32 v17, 0xbf1b4598, v17
	v_mul_f32_e32 v14, 0x3fb8aa3b, v14
	v_mul_f32_e32 v15, 0x3fb8aa3b, v15
	v_mul_f32_e32 v16, 0x3fb8aa3b, v16
	v_mul_f32_e32 v17, 0x3fb8aa3b, v17
	v_exp_f32_e32 v14, v14
	v_exp_f32_e32 v15, v15
	v_exp_f32_e32 v16, v16
	v_exp_f32_e32 v17, v17
	v_add_f32_e32 v152, -1.0, v18
	v_add_f32_e32 v153, -1.0, v19
	v_add_f32_e32 v154, -1.0, v20
	v_add_f32_e32 v155, -1.0, v21
	v_fma_f32 v152, v202, v152, 1.0
	v_fma_f32 v153, v203, v153, 1.0
	v_fma_f32 v154, v204, v154, 1.0
	v_fma_f32 v155, v205, v155, 1.0
	v_mul_f32_e32 v152, v136, v152
	v_mul_f32_e32 v153, v238, v153
	v_mul_f32_e32 v154, v137, v154
	v_mul_f32_e32 v155, v239, v155
	v_mul_f32_e32 v156, v134, v152
	v_mul_f32_e32 v157, v236, v153
	v_mul_f32_e32 v158, v135, v154
	v_mul_f32_e32 v159, v237, v155
	v_mul_f32_e32 v177, v206, v156
	v_fmac_f32_e32 v177, v207, v157
	v_fmac_f32_e32 v177, v208, v158
	v_fmac_f32_e32 v177, v209, v159
	v_mul_f32_e32 v148, v148, v178
	v_mul_f32_e32 v149, v149, v178
	v_add_f32_dpp v177, v177, v177 quad_perm:[1,0,3,2] row_mask:0xf bank_mask:0xf bound_ctrl:1
	v_mul_f32_e32 v150, v150, v178
	v_mul_f32_e32 v151, v151, v178
	v_add_f32_dpp v177, v177, v177 quad_perm:[2,3,0,1] row_mask:0xf bank_mask:0xf bound_ctrl:1
	v_mul_f32_e32 v18, v18, v148
	v_mul_f32_e32 v19, v19, v149
	v_add_f32_dpp v177, v177, v177 row_half_mirror row_mask:0xf bank_mask:0xf bound_ctrl:1
	v_mul_f32_e32 v20, v20, v150
	v_mul_f32_e32 v21, v21, v151
	v_add_f32_dpp v177, v177, v177 row_mirror row_mask:0xf bank_mask:0xf bound_ctrl:1
	s_lshl_b32 s0, s57, 9
	s_add_u32 s62, s34, s0
	s_addc_u32 s63, s35, 0
	v_fmac_f32_e32 v146, v138, v177
	v_fmac_f32_e32 v248, v240, v177
	v_fmac_f32_e32 v147, v139, v177
	v_fmac_f32_e32 v249, v241, v177
	v_cvt_pk_bf16_f32 v72, v134, v236
	v_cvt_pk_bf16_f32 v73, v135, v237
	global_store_dwordx2 v250, v[72:73], s[62:63]
	v_cvt_pk_bf16_f32 v74, v14, v15
	v_cvt_pk_bf16_f32 v75, v16, v17
	s_add_u32 s0, s62, 0x500000
	s_addc_u32 s1, s63, 0
	global_store_dwordx2 v250, v[74:75], s[0:1]
	v_cvt_pk_bf16_f32 v180, v152, v153
	v_cvt_pk_bf16_f32 v181, v154, v155
	s_add_u32 s0, s62, 0xa00000
	s_addc_u32 s1, s63, 0
	global_store_dwordx2 v250, v[180:181], s[0:1]
	v_cvt_pk_bf16_f32 v72, v138, v240
	v_cvt_pk_bf16_f32 v73, v139, v241
	s_add_u32 s0, s62, 0xf00000
	s_addc_u32 s1, s63, 0
	global_store_dwordx2 v250, v[72:73], s[0:1]
	v_cvt_pk_bf16_f32 v74, v148, v149
	v_cvt_pk_bf16_f32 v75, v150, v151
	s_add_u32 s0, s62, 0x1400000
	s_addc_u32 s1, s63, 0
	global_store_dwordx2 v250, v[74:75], s[0:1]
	v_cvt_pk_bf16_f32 v180, v18, v19
	v_cvt_pk_bf16_f32 v181, v20, v21
	s_add_u32 s0, s62, 0x1900000
	s_addc_u32 s1, s63, 0
	global_store_dwordx2 v250, v[180:181], s[0:1]
	v_cvt_pk_bf16_f32 v72, v146, v248
	v_cvt_pk_bf16_f32 v73, v147, v249
	s_lshl_b32 s0, s57, 9
	s_add_u32 s0, s42, s0
	s_addc_u32 s1, s43, 0
	global_store_dwordx2 v250, v[72:73], s[0:1]
	s_branch .LBB0_476
